# MFMA shadow fill: loop-tail pointer/counter increments moved into the last MFMA block of each K-loop iteration (on top of v26)
# baseline (speedup 1.0000x reference)
.LBB0_229:
	s_add_u32 s48, s46, 0xfffc0080
	s_addc_u32 s49, s47, -1
	s_add_i32 s63, 0, 0x10000
	s_cmp_eq_u32 s62, 12
	s_cselect_b32 s51, s39, s49
	s_cselect_b32 s50, s58, s48
	v_add_u32_e32 v0, s63, v144
	s_cselect_b32 s49, s23, s61
	s_cselect_b32 s48, s59, s60
	s_add_i32 s66, 0, 0x14000
	ds_read_b128 v[146:149], v0
	ds_read_b128 v[150:153], v0 offset:1024
	ds_read_b128 v[154:157], v0 offset:2048
	ds_read_b128 v[158:161], v0 offset:3072
	v_add_u32_e32 v0, s66, v144
	ds_read_b128 v[162:165], v0
	ds_read_b128 v[166:169], v0 offset:1024
	ds_read_b128 v[170:173], v0 offset:2048
	ds_read_b128 v[174:177], v0 offset:3072
	s_add_i32 m0, s5, 0xc000
	ds_read_b128 v[178:181], v145
	ds_read_b128 v[182:185], v145 offset:1024
	ds_read_b128 v[204:207], v145 offset:2048
	ds_read_b128 v[208:211], v145 offset:3072
	ds_read_b128 v[212:215], v145 offset:4096
	ds_read_b128 v[216:219], v145 offset:5120
	ds_read_b128 v[220:223], v145 offset:6144
	ds_read_b128 v[224:227], v145 offset:7168
	global_load_lds_dwordx4 v138, s[46:47]
	s_add_i32 m0, s5, 0xe000
	s_nop 0
	global_load_lds_dwordx4 v140, s[46:47]
	s_waitcnt vmcnt(8)
	s_waitcnt lgkmcnt(0)
	s_setprio 1
	s_barrier
	v_mfma_f32_16x16x32_bf16 v[118:121], v[146:149], v[178:181], v[118:121]
	v_mfma_f32_16x16x32_bf16 v[114:117], v[154:157], v[178:181], v[114:117]
	v_mfma_f32_16x16x32_bf16 v[110:113], v[146:149], v[204:207], v[110:113]
	v_mfma_f32_16x16x32_bf16 v[102:105], v[154:157], v[204:207], v[102:105]
	v_mfma_f32_16x16x32_bf16 v[94:97], v[146:149], v[212:215], v[94:97]
	v_mfma_f32_16x16x32_bf16 v[86:89], v[154:157], v[212:215], v[86:89]
	v_mfma_f32_16x16x32_bf16 v[78:81], v[146:149], v[220:223], v[78:81]
	v_mfma_f32_16x16x32_bf16 v[70:73], v[154:157], v[220:223], v[70:73]
	v_mfma_f32_16x16x32_bf16 v[118:121], v[150:153], v[182:185], v[118:121]
	v_mfma_f32_16x16x32_bf16 v[114:117], v[158:161], v[182:185], v[114:117]
	v_mfma_f32_16x16x32_bf16 v[110:113], v[150:153], v[208:211], v[110:113]
	v_mfma_f32_16x16x32_bf16 v[102:105], v[158:161], v[208:211], v[102:105]
	v_mfma_f32_16x16x32_bf16 v[94:97], v[150:153], v[216:219], v[94:97]
	v_mfma_f32_16x16x32_bf16 v[86:89], v[158:161], v[216:219], v[86:89]
	v_mfma_f32_16x16x32_bf16 v[78:81], v[150:153], v[224:227], v[78:81]
	v_mfma_f32_16x16x32_bf16 v[70:73], v[158:161], v[224:227], v[70:73]
	v_mfma_f32_16x16x32_bf16 v[126:129], v[162:165], v[178:181], v[126:129]
	v_mfma_f32_16x16x32_bf16 v[122:125], v[170:173], v[178:181], v[122:125]
	v_mfma_f32_16x16x32_bf16 v[106:109], v[162:165], v[204:207], v[106:109]
	v_mfma_f32_16x16x32_bf16 v[98:101], v[170:173], v[204:207], v[98:101]
	v_mfma_f32_16x16x32_bf16 v[90:93], v[162:165], v[212:215], v[90:93]
	v_mfma_f32_16x16x32_bf16 v[82:85], v[170:173], v[212:215], v[82:85]
	v_mfma_f32_16x16x32_bf16 v[74:77], v[162:165], v[220:223], v[74:77]
	v_mfma_f32_16x16x32_bf16 v[66:69], v[170:173], v[220:223], v[66:69]
	v_mfma_f32_16x16x32_bf16 v[126:129], v[166:169], v[182:185], v[126:129]
	v_mfma_f32_16x16x32_bf16 v[122:125], v[174:177], v[182:185], v[122:125]
	v_mfma_f32_16x16x32_bf16 v[106:109], v[166:169], v[208:211], v[106:109]
	v_mfma_f32_16x16x32_bf16 v[98:101], v[174:177], v[208:211], v[98:101]
	v_mfma_f32_16x16x32_bf16 v[90:93], v[166:169], v[216:219], v[90:93]
	v_mfma_f32_16x16x32_bf16 v[82:85], v[174:177], v[216:219], v[82:85]
	v_mfma_f32_16x16x32_bf16 v[74:77], v[166:169], v[224:227], v[74:77]
	v_mfma_f32_16x16x32_bf16 v[66:69], v[174:177], v[224:227], v[66:69]
	s_barrier
	s_setprio 0
	s_add_i32 s63, s63, s4
	s_mov_b32 m0, s63
	ds_read_b128 v[178:181], v145 offset:16384
	ds_read_b128 v[182:185], v145 offset:17408
	ds_read_b128 v[204:207], v145 offset:18432
	ds_read_b128 v[208:211], v145 offset:19456
	ds_read_b128 v[212:215], v145 offset:20480
	ds_read_b128 v[216:219], v145 offset:21504
	ds_read_b128 v[220:223], v145 offset:22528
	ds_read_b128 v[224:227], v145 offset:23552
	global_load_lds_dwordx4 v134, s[48:49]
	s_add_i32 m0, s63, 0x2000
	s_add_u32 s64, s48, 0x40000
	s_addc_u32 s65, s49, 0
	s_add_i32 s63, s66, s4
	global_load_lds_dwordx4 v130, s[48:49]
	s_mov_b32 m0, s63
	s_nop 0
	global_load_lds_dwordx4 v134, s[64:65]
	s_add_i32 m0, s63, 0x2000
	s_nop 0
	global_load_lds_dwordx4 v130, s[64:65]
	s_mov_b32 m0, s5
	s_nop 0
	global_load_lds_dwordx4 v136, s[50:51]
	s_mov_b32 m0, s6
	s_nop 0
	global_load_lds_dwordx4 v132, s[50:51]
	s_waitcnt vmcnt(8)
	s_waitcnt lgkmcnt(0)
	s_setprio 1
	s_barrier
	v_mfma_f32_16x16x32_bf16 v[62:65], v[146:149], v[178:181], v[62:65]
	v_mfma_f32_16x16x32_bf16 v[54:57], v[154:157], v[178:181], v[54:57]
	v_mfma_f32_16x16x32_bf16 v[46:49], v[146:149], v[204:207], v[46:49]
	v_mfma_f32_16x16x32_bf16 v[38:41], v[154:157], v[204:207], v[38:41]
	v_mfma_f32_16x16x32_bf16 v[30:33], v[146:149], v[212:215], v[30:33]
	v_mfma_f32_16x16x32_bf16 v[22:25], v[154:157], v[212:215], v[22:25]
	v_mfma_f32_16x16x32_bf16 v[14:17], v[146:149], v[220:223], v[14:17]
	v_mfma_f32_16x16x32_bf16 v[6:9], v[154:157], v[220:223], v[6:9]
	v_mfma_f32_16x16x32_bf16 v[62:65], v[150:153], v[182:185], v[62:65]
	v_mfma_f32_16x16x32_bf16 v[54:57], v[158:161], v[182:185], v[54:57]
	v_mfma_f32_16x16x32_bf16 v[46:49], v[150:153], v[208:211], v[46:49]
	v_mfma_f32_16x16x32_bf16 v[38:41], v[158:161], v[208:211], v[38:41]
	v_mfma_f32_16x16x32_bf16 v[30:33], v[150:153], v[216:219], v[30:33]
	v_mfma_f32_16x16x32_bf16 v[22:25], v[158:161], v[216:219], v[22:25]
	v_mfma_f32_16x16x32_bf16 v[14:17], v[150:153], v[224:227], v[14:17]
	v_mfma_f32_16x16x32_bf16 v[6:9], v[158:161], v[224:227], v[6:9]
	v_mfma_f32_16x16x32_bf16 v[58:61], v[162:165], v[178:181], v[58:61]
	v_mfma_f32_16x16x32_bf16 v[50:53], v[170:173], v[178:181], v[50:53]
	v_mfma_f32_16x16x32_bf16 v[42:45], v[162:165], v[204:207], v[42:45]
	v_mfma_f32_16x16x32_bf16 v[34:37], v[170:173], v[204:207], v[34:37]
	v_mfma_f32_16x16x32_bf16 v[26:29], v[162:165], v[212:215], v[26:29]
	v_mfma_f32_16x16x32_bf16 v[18:21], v[170:173], v[212:215], v[18:21]
	v_mfma_f32_16x16x32_bf16 v[10:13], v[162:165], v[220:223], v[10:13]
	v_mfma_f32_16x16x32_bf16 v[2:5], v[170:173], v[220:223], v[2:5]
	v_mfma_f32_16x16x32_bf16 v[58:61], v[166:169], v[182:185], v[58:61]
	v_mfma_f32_16x16x32_bf16 v[50:53], v[174:177], v[182:185], v[50:53]
	v_mfma_f32_16x16x32_bf16 v[42:45], v[166:169], v[208:211], v[42:45]
	v_mfma_f32_16x16x32_bf16 v[34:37], v[174:177], v[208:211], v[34:37]
	v_mfma_f32_16x16x32_bf16 v[26:29], v[166:169], v[216:219], v[26:29]
	v_mfma_f32_16x16x32_bf16 v[18:21], v[174:177], v[216:219], v[18:21]
	v_mfma_f32_16x16x32_bf16 v[10:13], v[166:169], v[224:227], v[10:13]
	v_mfma_f32_16x16x32_bf16 v[2:5], v[174:177], v[224:227], v[2:5]
	s_barrier
	s_setprio 0
	s_add_i32 s63, 0, 0x18000
	v_add_u32_e32 v0, s63, v144
	s_add_i32 s64, 0, 0x1c000
	ds_read_b128 v[146:149], v0
	ds_read_b128 v[150:153], v0 offset:1024
	ds_read_b128 v[154:157], v0 offset:2048
	ds_read_b128 v[158:161], v0 offset:3072
	v_add_u32_e32 v0, s64, v144
	ds_read_b128 v[162:165], v0
	ds_read_b128 v[166:169], v0 offset:1024
	ds_read_b128 v[170:173], v0 offset:2048
	ds_read_b128 v[174:177], v0 offset:3072
	s_add_u32 s50, s50, 0x40000
	s_addc_u32 s51, s51, 0
	s_mov_b32 m0, s7
	ds_read_b128 v[178:181], v145 offset:32768
	ds_read_b128 v[182:185], v145 offset:33792
	ds_read_b128 v[204:207], v145 offset:34816
	ds_read_b128 v[208:211], v145 offset:35840
	ds_read_b128 v[212:215], v145 offset:36864
	ds_read_b128 v[216:219], v145 offset:37888
	ds_read_b128 v[220:223], v145 offset:38912
	ds_read_b128 v[224:227], v145 offset:39936
	global_load_lds_dwordx4 v136, s[50:51]
	s_mov_b32 m0, s52
	s_nop 0
	global_load_lds_dwordx4 v132, s[50:51]
	s_waitcnt vmcnt(8)
	s_waitcnt lgkmcnt(0)
	s_setprio 1
	s_barrier
	v_mfma_f32_16x16x32_bf16 v[118:121], v[146:149], v[178:181], v[118:121]
	v_mfma_f32_16x16x32_bf16 v[114:117], v[154:157], v[178:181], v[114:117]
	v_mfma_f32_16x16x32_bf16 v[110:113], v[146:149], v[204:207], v[110:113]
	v_mfma_f32_16x16x32_bf16 v[102:105], v[154:157], v[204:207], v[102:105]
	v_mfma_f32_16x16x32_bf16 v[94:97], v[146:149], v[212:215], v[94:97]
	v_mfma_f32_16x16x32_bf16 v[86:89], v[154:157], v[212:215], v[86:89]
	v_mfma_f32_16x16x32_bf16 v[78:81], v[146:149], v[220:223], v[78:81]
	v_mfma_f32_16x16x32_bf16 v[70:73], v[154:157], v[220:223], v[70:73]
	v_mfma_f32_16x16x32_bf16 v[118:121], v[150:153], v[182:185], v[118:121]
	v_mfma_f32_16x16x32_bf16 v[114:117], v[158:161], v[182:185], v[114:117]
	v_mfma_f32_16x16x32_bf16 v[110:113], v[150:153], v[208:211], v[110:113]
	v_mfma_f32_16x16x32_bf16 v[102:105], v[158:161], v[208:211], v[102:105]
	v_mfma_f32_16x16x32_bf16 v[94:97], v[150:153], v[216:219], v[94:97]
	v_mfma_f32_16x16x32_bf16 v[86:89], v[158:161], v[216:219], v[86:89]
	v_mfma_f32_16x16x32_bf16 v[78:81], v[150:153], v[224:227], v[78:81]
	v_mfma_f32_16x16x32_bf16 v[70:73], v[158:161], v[224:227], v[70:73]
	v_mfma_f32_16x16x32_bf16 v[126:129], v[162:165], v[178:181], v[126:129]
	v_mfma_f32_16x16x32_bf16 v[122:125], v[170:173], v[178:181], v[122:125]
	v_mfma_f32_16x16x32_bf16 v[106:109], v[162:165], v[204:207], v[106:109]
	v_mfma_f32_16x16x32_bf16 v[98:101], v[170:173], v[204:207], v[98:101]
	v_mfma_f32_16x16x32_bf16 v[90:93], v[162:165], v[212:215], v[90:93]
	v_mfma_f32_16x16x32_bf16 v[82:85], v[170:173], v[212:215], v[82:85]
	v_mfma_f32_16x16x32_bf16 v[74:77], v[162:165], v[220:223], v[74:77]
	v_mfma_f32_16x16x32_bf16 v[66:69], v[170:173], v[220:223], v[66:69]
	v_mfma_f32_16x16x32_bf16 v[126:129], v[166:169], v[182:185], v[126:129]
	v_mfma_f32_16x16x32_bf16 v[122:125], v[174:177], v[182:185], v[122:125]
	v_mfma_f32_16x16x32_bf16 v[106:109], v[166:169], v[208:211], v[106:109]
	v_mfma_f32_16x16x32_bf16 v[98:101], v[174:177], v[208:211], v[98:101]
	v_mfma_f32_16x16x32_bf16 v[90:93], v[166:169], v[216:219], v[90:93]
	v_mfma_f32_16x16x32_bf16 v[82:85], v[174:177], v[216:219], v[82:85]
	v_mfma_f32_16x16x32_bf16 v[74:77], v[166:169], v[224:227], v[74:77]
	v_mfma_f32_16x16x32_bf16 v[66:69], v[174:177], v[224:227], v[66:69]
	s_barrier
	s_setprio 0
	s_add_i32 s65, s63, s4
	s_add_u32 s48, s48, 0x80
	s_addc_u32 s49, s49, 0
	s_mov_b32 m0, s65
	ds_read_b128 v[178:181], v145 offset:49152
	ds_read_b128 v[182:185], v145 offset:50176
	ds_read_b128 v[204:207], v145 offset:51200
	ds_read_b128 v[208:211], v145 offset:52224
	ds_read_b128 v[212:215], v145 offset:53248
	ds_read_b128 v[216:219], v145 offset:54272
	ds_read_b128 v[220:223], v145 offset:55296
	ds_read_b128 v[224:227], v145 offset:56320
	global_load_lds_dwordx4 v134, s[48:49]
	s_add_i32 m0, s65, 0x2000
	s_add_i32 s65, s64, s4
	global_load_lds_dwordx4 v130, s[48:49]
	s_add_u32 s48, s48, 0x40000
	s_addc_u32 s49, s49, 0
	s_mov_b32 m0, s65
	s_sub_u32 s50, s50, 0x3ff80
	global_load_lds_dwordx4 v134, s[48:49]
	s_subb_u32 s51, s51, 0
	s_add_i32 m0, s65, 0x2000
	s_nop 0
	global_load_lds_dwordx4 v130, s[48:49]
	s_mov_b32 m0, s55
	s_nop 0
	global_load_lds_dwordx4 v136, s[50:51]
	s_mov_b32 m0, s56
	s_nop 0
	global_load_lds_dwordx4 v132, s[50:51]
	s_waitcnt vmcnt(8)
	s_waitcnt lgkmcnt(0)
	s_setprio 1
	s_barrier
	v_mfma_f32_16x16x32_bf16 v[62:65], v[146:149], v[178:181], v[62:65]
	v_mfma_f32_16x16x32_bf16 v[54:57], v[154:157], v[178:181], v[54:57]
	v_mfma_f32_16x16x32_bf16 v[46:49], v[146:149], v[204:207], v[46:49]
	v_mfma_f32_16x16x32_bf16 v[38:41], v[154:157], v[204:207], v[38:41]
	v_mfma_f32_16x16x32_bf16 v[30:33], v[146:149], v[212:215], v[30:33]
	v_mfma_f32_16x16x32_bf16 v[22:25], v[154:157], v[212:215], v[22:25]
	v_mfma_f32_16x16x32_bf16 v[14:17], v[146:149], v[220:223], v[14:17]
	v_mfma_f32_16x16x32_bf16 v[6:9], v[154:157], v[220:223], v[6:9]
	s_add_i32 s62, s62, 2
	s_add_u32 s46, s46, 0x100
	s_addc_u32 s47, s47, 0
	s_add_u32 s60, s60, 0x100
	s_addc_u32 s61, s61, 0
	v_mfma_f32_16x16x32_bf16 v[62:65], v[150:153], v[182:185], v[62:65]
	v_mfma_f32_16x16x32_bf16 v[54:57], v[158:161], v[182:185], v[54:57]
	v_mfma_f32_16x16x32_bf16 v[46:49], v[150:153], v[208:211], v[46:49]
	v_mfma_f32_16x16x32_bf16 v[38:41], v[158:161], v[208:211], v[38:41]
	v_mfma_f32_16x16x32_bf16 v[30:33], v[150:153], v[216:219], v[30:33]
	v_mfma_f32_16x16x32_bf16 v[22:25], v[158:161], v[216:219], v[22:25]
	v_mfma_f32_16x16x32_bf16 v[14:17], v[150:153], v[224:227], v[14:17]
	v_mfma_f32_16x16x32_bf16 v[6:9], v[158:161], v[224:227], v[6:9]
	v_mfma_f32_16x16x32_bf16 v[58:61], v[162:165], v[178:181], v[58:61]
	v_mfma_f32_16x16x32_bf16 v[50:53], v[170:173], v[178:181], v[50:53]
	v_mfma_f32_16x16x32_bf16 v[42:45], v[162:165], v[204:207], v[42:45]
	v_mfma_f32_16x16x32_bf16 v[34:37], v[170:173], v[204:207], v[34:37]
	v_mfma_f32_16x16x32_bf16 v[26:29], v[162:165], v[212:215], v[26:29]
	v_mfma_f32_16x16x32_bf16 v[18:21], v[170:173], v[212:215], v[18:21]
	v_mfma_f32_16x16x32_bf16 v[10:13], v[162:165], v[220:223], v[10:13]
	v_mfma_f32_16x16x32_bf16 v[2:5], v[170:173], v[220:223], v[2:5]
	v_mfma_f32_16x16x32_bf16 v[58:61], v[166:169], v[182:185], v[58:61]
	v_mfma_f32_16x16x32_bf16 v[50:53], v[174:177], v[182:185], v[50:53]
	v_mfma_f32_16x16x32_bf16 v[42:45], v[166:169], v[208:211], v[42:45]
	v_mfma_f32_16x16x32_bf16 v[34:37], v[174:177], v[208:211], v[34:37]
	v_mfma_f32_16x16x32_bf16 v[26:29], v[166:169], v[216:219], v[26:29]
	v_mfma_f32_16x16x32_bf16 v[18:21], v[174:177], v[216:219], v[18:21]
	v_mfma_f32_16x16x32_bf16 v[10:13], v[166:169], v[224:227], v[10:13]
	v_mfma_f32_16x16x32_bf16 v[2:5], v[174:177], v[224:227], v[2:5]
	s_barrier
	s_setprio 0
	s_cmp_gt_u32 s62, 13
	s_cbranch_scc0 .LBB0_229
	s_and_b64 vcc, exec, s[20:21]
	s_cbranch_vccz .LBB0_232
	s_barrier

.LBB0_320:
	s_add_u32 s0, s48, 0x100
	s_addc_u32 s1, s49, 0
	s_add_i32 s51, 0, 0x10000
	s_cmp_eq_u32 s19, 40
	s_cselect_b32 s55, s45, s1
	s_cselect_b32 s54, s44, s0
	v_add_u32_e32 v0, s51, v219
	s_cselect_b32 s53, s47, s18
	s_cselect_b32 s52, s46, s7
	s_add_i32 s66, 0, 0x14000
	ds_read_b128 v[106:109], v0
	ds_read_b128 v[110:113], v0 offset:1024
	ds_read_b128 v[126:129], v0 offset:2048
	ds_read_b128 v[134:137], v0 offset:3072
	v_add_u32_e32 v0, s66, v219
	ds_read_b128 v[146:149], v0
	ds_read_b128 v[150:153], v0 offset:1024
	ds_read_b128 v[154:157], v0 offset:2048
	ds_read_b128 v[158:161], v0 offset:3072
	v_lshl_add_u64 v[216:217], s[48:49], 0, v[212:213]
	s_add_i32 m0, s57, 0xc000
	ds_read_b128 v[162:165], v220
	ds_read_b128 v[166:169], v220 offset:1024
	ds_read_b128 v[170:173], v220 offset:2048
	ds_read_b128 v[174:177], v220 offset:3072
	ds_read_b128 v[178:181], v220 offset:4096
	ds_read_b128 v[182:185], v220 offset:5120
	ds_read_b128 v[222:225], v220 offset:6144
	ds_read_b128 v[226:229], v220 offset:7168
	global_load_lds_dwordx4 v[216:217], off
	v_lshl_add_u64 v[216:217], s[48:49], 0, v[214:215]
	s_add_i32 m0, s57, 0xe000
	s_nop 0
	global_load_lds_dwordx4 v[216:217], off
	s_waitcnt vmcnt(8)
	s_waitcnt lgkmcnt(0)
	s_setprio 1
	s_barrier
	v_mfma_f32_16x16x32_bf16 v[142:145], v[106:109], v[162:165], v[142:145]
	v_mfma_f32_16x16x32_bf16 v[138:141], v[126:129], v[162:165], v[138:141]
	v_mfma_f32_16x16x32_bf16 v[118:121], v[106:109], v[170:173], v[118:121]
	v_mfma_f32_16x16x32_bf16 v[114:117], v[126:129], v[170:173], v[114:117]
	v_mfma_f32_16x16x32_bf16 v[94:97], v[106:109], v[178:181], v[94:97]
	v_mfma_f32_16x16x32_bf16 v[90:93], v[126:129], v[178:181], v[90:93]
	v_mfma_f32_16x16x32_bf16 v[78:81], v[106:109], v[222:225], v[78:81]
	v_mfma_f32_16x16x32_bf16 v[74:77], v[126:129], v[222:225], v[74:77]
	v_mfma_f32_16x16x32_bf16 v[142:145], v[110:113], v[166:169], v[142:145]
	v_mfma_f32_16x16x32_bf16 v[138:141], v[134:137], v[166:169], v[138:141]
	v_mfma_f32_16x16x32_bf16 v[118:121], v[110:113], v[174:177], v[118:121]
	v_mfma_f32_16x16x32_bf16 v[114:117], v[134:137], v[174:177], v[114:117]
	v_mfma_f32_16x16x32_bf16 v[94:97], v[110:113], v[182:185], v[94:97]
	v_mfma_f32_16x16x32_bf16 v[90:93], v[134:137], v[182:185], v[90:93]
	v_mfma_f32_16x16x32_bf16 v[78:81], v[110:113], v[226:229], v[78:81]
	v_mfma_f32_16x16x32_bf16 v[74:77], v[134:137], v[226:229], v[74:77]
	v_mfma_f32_16x16x32_bf16 v[130:133], v[146:149], v[162:165], v[130:133]
	v_mfma_f32_16x16x32_bf16 v[122:125], v[154:157], v[162:165], v[122:125]
	v_mfma_f32_16x16x32_bf16 v[102:105], v[146:149], v[170:173], v[102:105]
	v_mfma_f32_16x16x32_bf16 v[98:101], v[154:157], v[170:173], v[98:101]
	v_mfma_f32_16x16x32_bf16 v[86:89], v[146:149], v[178:181], v[86:89]
	v_mfma_f32_16x16x32_bf16 v[82:85], v[154:157], v[178:181], v[82:85]
	v_mfma_f32_16x16x32_bf16 v[70:73], v[146:149], v[222:225], v[70:73]
	v_mfma_f32_16x16x32_bf16 v[66:69], v[154:157], v[222:225], v[66:69]
	v_mfma_f32_16x16x32_bf16 v[130:133], v[150:153], v[166:169], v[130:133]
	v_mfma_f32_16x16x32_bf16 v[122:125], v[158:161], v[166:169], v[122:125]
	v_mfma_f32_16x16x32_bf16 v[102:105], v[150:153], v[174:177], v[102:105]
	v_mfma_f32_16x16x32_bf16 v[98:101], v[158:161], v[174:177], v[98:101]
	v_mfma_f32_16x16x32_bf16 v[86:89], v[150:153], v[182:185], v[86:89]
	v_mfma_f32_16x16x32_bf16 v[82:85], v[158:161], v[182:185], v[82:85]
	v_mfma_f32_16x16x32_bf16 v[70:73], v[150:153], v[226:229], v[70:73]
	v_mfma_f32_16x16x32_bf16 v[66:69], v[158:161], v[226:229], v[66:69]
	s_barrier
	s_setprio 0
	s_add_i32 s48, s51, s56
	v_lshl_add_u64 v[216:217], s[52:53], 0, v[208:209]
	s_mov_b32 m0, s48
	ds_read_b128 v[162:165], v220 offset:16384
	ds_read_b128 v[166:169], v220 offset:17408
	ds_read_b128 v[170:173], v220 offset:18432
	ds_read_b128 v[174:177], v220 offset:19456
	ds_read_b128 v[178:181], v220 offset:20480
	ds_read_b128 v[182:185], v220 offset:21504
	ds_read_b128 v[222:225], v220 offset:22528
	ds_read_b128 v[226:229], v220 offset:23552
	global_load_lds_dwordx4 v[216:217], off
	s_add_i32 m0, s48, 0x2000
	s_add_u32 s48, s52, 0xb0000
	v_lshl_add_u64 v[230:231], s[52:53], 0, v[204:205]
	s_addc_u32 s49, s53, 0
	s_add_i32 s51, s66, s56
	global_load_lds_dwordx4 v[230:231], off
	v_lshl_add_u64 v[240:241], s[48:49], 0, v[208:209]
	s_mov_b32 m0, s51
	v_lshl_add_u64 v[242:243], s[54:55], 0, v[206:207]
	global_load_lds_dwordx4 v[240:241], off
	v_lshl_add_u64 v[240:241], s[48:49], 0, v[204:205]
	s_add_i32 m0, s51, 0x2000
	s_nop 0
	global_load_lds_dwordx4 v[240:241], off
	v_lshl_add_u64 v[240:241], s[54:55], 0, v[210:211]
	s_mov_b32 m0, s57
	s_nop 0
	global_load_lds_dwordx4 v[240:241], off
	s_mov_b32 m0, s58
	s_nop 0
	global_load_lds_dwordx4 v[242:243], off
	s_waitcnt vmcnt(8)
	s_waitcnt lgkmcnt(0)
	s_setprio 1
	s_barrier
	v_mfma_f32_16x16x32_bf16 v[62:65], v[106:109], v[162:165], v[62:65]
	v_mfma_f32_16x16x32_bf16 v[58:61], v[126:129], v[162:165], v[58:61]
	v_mfma_f32_16x16x32_bf16 v[46:49], v[106:109], v[170:173], v[46:49]
	v_mfma_f32_16x16x32_bf16 v[42:45], v[126:129], v[170:173], v[42:45]
	v_mfma_f32_16x16x32_bf16 v[30:33], v[106:109], v[178:181], v[30:33]
	v_mfma_f32_16x16x32_bf16 v[26:29], v[126:129], v[178:181], v[26:29]
	v_mfma_f32_16x16x32_bf16 v[14:17], v[106:109], v[222:225], v[14:17]
	v_mfma_f32_16x16x32_bf16 v[10:13], v[126:129], v[222:225], v[10:13]
	v_mfma_f32_16x16x32_bf16 v[62:65], v[110:113], v[166:169], v[62:65]
	v_mfma_f32_16x16x32_bf16 v[58:61], v[134:137], v[166:169], v[58:61]
	v_mfma_f32_16x16x32_bf16 v[46:49], v[110:113], v[174:177], v[46:49]
	v_mfma_f32_16x16x32_bf16 v[42:45], v[134:137], v[174:177], v[42:45]
	v_mfma_f32_16x16x32_bf16 v[30:33], v[110:113], v[182:185], v[30:33]
	v_mfma_f32_16x16x32_bf16 v[26:29], v[134:137], v[182:185], v[26:29]
	v_mfma_f32_16x16x32_bf16 v[14:17], v[110:113], v[226:229], v[14:17]
	v_mfma_f32_16x16x32_bf16 v[10:13], v[134:137], v[226:229], v[10:13]
	v_mfma_f32_16x16x32_bf16 v[54:57], v[146:149], v[162:165], v[54:57]
	v_mfma_f32_16x16x32_bf16 v[50:53], v[154:157], v[162:165], v[50:53]
	v_mfma_f32_16x16x32_bf16 v[38:41], v[146:149], v[170:173], v[38:41]
	v_mfma_f32_16x16x32_bf16 v[34:37], v[154:157], v[170:173], v[34:37]
	v_mfma_f32_16x16x32_bf16 v[22:25], v[146:149], v[178:181], v[22:25]
	v_mfma_f32_16x16x32_bf16 v[18:21], v[154:157], v[178:181], v[18:21]
	v_mfma_f32_16x16x32_bf16 v[6:9], v[146:149], v[222:225], v[6:9]
	v_mfma_f32_16x16x32_bf16 v[2:5], v[154:157], v[222:225], v[2:5]
	v_mfma_f32_16x16x32_bf16 v[54:57], v[150:153], v[166:169], v[54:57]
	v_mfma_f32_16x16x32_bf16 v[50:53], v[158:161], v[166:169], v[50:53]
	v_mfma_f32_16x16x32_bf16 v[38:41], v[150:153], v[174:177], v[38:41]
	v_mfma_f32_16x16x32_bf16 v[34:37], v[158:161], v[174:177], v[34:37]
	v_mfma_f32_16x16x32_bf16 v[22:25], v[150:153], v[182:185], v[22:25]
	v_mfma_f32_16x16x32_bf16 v[18:21], v[158:161], v[182:185], v[18:21]
	v_mfma_f32_16x16x32_bf16 v[6:9], v[150:153], v[226:229], v[6:9]
	v_mfma_f32_16x16x32_bf16 v[2:5], v[158:161], v[226:229], v[2:5]
	s_barrier
	s_setprio 0
	s_add_i32 s51, 0, 0x18000
	v_add_u32_e32 v0, s51, v219
	s_add_i32 s66, 0, 0x1c000
	ds_read_b128 v[106:109], v0
	ds_read_b128 v[110:113], v0 offset:1024
	ds_read_b128 v[126:129], v0 offset:2048
	ds_read_b128 v[134:137], v0 offset:3072
	v_add_u32_e32 v0, s66, v219
	ds_read_b128 v[146:149], v0
	ds_read_b128 v[150:153], v0 offset:1024
	ds_read_b128 v[154:157], v0 offset:2048
	ds_read_b128 v[158:161], v0 offset:3072
	s_add_u32 s48, s54, 0xb0000
	s_addc_u32 s49, s55, 0
	s_mov_b32 m0, s59
	v_lshl_add_u64 v[244:245], s[48:49], 0, v[210:211]
	ds_read_b128 v[162:165], v220 offset:32768
	ds_read_b128 v[166:169], v220 offset:33792
	ds_read_b128 v[170:173], v220 offset:34816
	ds_read_b128 v[174:177], v220 offset:35840
	ds_read_b128 v[178:181], v220 offset:36864
	ds_read_b128 v[182:185], v220 offset:37888
	ds_read_b128 v[222:225], v220 offset:38912
	ds_read_b128 v[226:229], v220 offset:39936
	global_load_lds_dwordx4 v[244:245], off
	v_lshl_add_u64 v[244:245], s[48:49], 0, v[206:207]
	s_mov_b32 m0, s60
	s_nop 0
	global_load_lds_dwordx4 v[244:245], off
	s_waitcnt vmcnt(8)
	s_waitcnt lgkmcnt(0)
	s_setprio 1
	s_barrier
	v_mfma_f32_16x16x32_bf16 v[142:145], v[106:109], v[162:165], v[142:145]
	v_mfma_f32_16x16x32_bf16 v[138:141], v[126:129], v[162:165], v[138:141]
	v_mfma_f32_16x16x32_bf16 v[118:121], v[106:109], v[170:173], v[118:121]
	v_mfma_f32_16x16x32_bf16 v[114:117], v[126:129], v[170:173], v[114:117]
	v_mfma_f32_16x16x32_bf16 v[94:97], v[106:109], v[178:181], v[94:97]
	v_mfma_f32_16x16x32_bf16 v[90:93], v[126:129], v[178:181], v[90:93]
	v_mfma_f32_16x16x32_bf16 v[78:81], v[106:109], v[222:225], v[78:81]
	v_mfma_f32_16x16x32_bf16 v[74:77], v[126:129], v[222:225], v[74:77]
	v_mfma_f32_16x16x32_bf16 v[142:145], v[110:113], v[166:169], v[142:145]
	v_mfma_f32_16x16x32_bf16 v[138:141], v[134:137], v[166:169], v[138:141]
	v_mfma_f32_16x16x32_bf16 v[118:121], v[110:113], v[174:177], v[118:121]
	v_mfma_f32_16x16x32_bf16 v[114:117], v[134:137], v[174:177], v[114:117]
	v_mfma_f32_16x16x32_bf16 v[94:97], v[110:113], v[182:185], v[94:97]
	v_mfma_f32_16x16x32_bf16 v[90:93], v[134:137], v[182:185], v[90:93]
	v_mfma_f32_16x16x32_bf16 v[78:81], v[110:113], v[226:229], v[78:81]
	v_mfma_f32_16x16x32_bf16 v[74:77], v[134:137], v[226:229], v[74:77]
	v_mfma_f32_16x16x32_bf16 v[130:133], v[146:149], v[162:165], v[130:133]
	v_mfma_f32_16x16x32_bf16 v[122:125], v[154:157], v[162:165], v[122:125]
	v_mfma_f32_16x16x32_bf16 v[102:105], v[146:149], v[170:173], v[102:105]
	v_mfma_f32_16x16x32_bf16 v[98:101], v[154:157], v[170:173], v[98:101]
	v_mfma_f32_16x16x32_bf16 v[86:89], v[146:149], v[178:181], v[86:89]
	v_mfma_f32_16x16x32_bf16 v[82:85], v[154:157], v[178:181], v[82:85]
	v_mfma_f32_16x16x32_bf16 v[70:73], v[146:149], v[222:225], v[70:73]
	v_mfma_f32_16x16x32_bf16 v[66:69], v[154:157], v[222:225], v[66:69]
	v_mfma_f32_16x16x32_bf16 v[130:133], v[150:153], v[166:169], v[130:133]
	v_mfma_f32_16x16x32_bf16 v[122:125], v[158:161], v[166:169], v[122:125]
	v_mfma_f32_16x16x32_bf16 v[102:105], v[150:153], v[174:177], v[102:105]
	v_mfma_f32_16x16x32_bf16 v[98:101], v[158:161], v[174:177], v[98:101]
	v_mfma_f32_16x16x32_bf16 v[86:89], v[150:153], v[182:185], v[86:89]
	v_mfma_f32_16x16x32_bf16 v[82:85], v[158:161], v[182:185], v[82:85]
	v_mfma_f32_16x16x32_bf16 v[70:73], v[150:153], v[226:229], v[70:73]
	v_mfma_f32_16x16x32_bf16 v[66:69], v[158:161], v[226:229], v[66:69]
	s_barrier
	s_setprio 0
	s_add_i32 s48, s51, s56
	v_lshl_add_u64 v[216:217], v[216:217], 0, s[16:17]
	s_mov_b32 m0, s48
	ds_read_b128 v[162:165], v220 offset:49152
	ds_read_b128 v[166:169], v220 offset:50176
	ds_read_b128 v[170:173], v220 offset:51200
	ds_read_b128 v[174:177], v220 offset:52224
	ds_read_b128 v[178:181], v220 offset:53248
	ds_read_b128 v[182:185], v220 offset:54272
	ds_read_b128 v[222:225], v220 offset:55296
	ds_read_b128 v[226:229], v220 offset:56320
	global_load_lds_dwordx4 v[216:217], off
	s_add_i32 m0, s48, 0x2000
	s_add_u32 s48, s52, 0xb0080
	v_lshl_add_u64 v[216:217], v[230:231], 0, s[16:17]
	s_addc_u32 s49, s53, 0
	s_add_i32 s51, s66, s56
	global_load_lds_dwordx4 v[216:217], off
	v_lshl_add_u64 v[216:217], s[48:49], 0, v[208:209]
	s_mov_b32 m0, s51
	s_nop 0
	global_load_lds_dwordx4 v[216:217], off
	v_lshl_add_u64 v[216:217], s[48:49], 0, v[204:205]
	s_add_i32 m0, s51, 0x2000
	s_nop 0
	global_load_lds_dwordx4 v[216:217], off
	v_lshl_add_u64 v[216:217], v[240:241], 0, s[16:17]
	s_mov_b32 m0, s63
	s_nop 0
	global_load_lds_dwordx4 v[216:217], off
	v_lshl_add_u64 v[216:217], v[242:243], 0, s[16:17]
	s_mov_b32 m0, s64
	s_nop 0
	global_load_lds_dwordx4 v[216:217], off
	s_waitcnt vmcnt(8)
	s_waitcnt lgkmcnt(0)
	s_setprio 1
	s_barrier
	v_mfma_f32_16x16x32_bf16 v[62:65], v[106:109], v[162:165], v[62:65]
	v_mfma_f32_16x16x32_bf16 v[58:61], v[126:129], v[162:165], v[58:61]
	v_mfma_f32_16x16x32_bf16 v[46:49], v[106:109], v[170:173], v[46:49]
	v_mfma_f32_16x16x32_bf16 v[42:45], v[126:129], v[170:173], v[42:45]
	v_mfma_f32_16x16x32_bf16 v[30:33], v[106:109], v[178:181], v[30:33]
	v_mfma_f32_16x16x32_bf16 v[26:29], v[126:129], v[178:181], v[26:29]
	v_mfma_f32_16x16x32_bf16 v[14:17], v[106:109], v[222:225], v[14:17]
	v_mfma_f32_16x16x32_bf16 v[10:13], v[126:129], v[222:225], v[10:13]
	s_add_i32 s19, s19, 2
	s_add_u32 s7, s7, 0x100
	s_addc_u32 s18, s18, 0
	v_mfma_f32_16x16x32_bf16 v[62:65], v[110:113], v[166:169], v[62:65]
	v_mfma_f32_16x16x32_bf16 v[58:61], v[134:137], v[166:169], v[58:61]
	v_mfma_f32_16x16x32_bf16 v[46:49], v[110:113], v[174:177], v[46:49]
	v_mfma_f32_16x16x32_bf16 v[42:45], v[134:137], v[174:177], v[42:45]
	v_mfma_f32_16x16x32_bf16 v[30:33], v[110:113], v[182:185], v[30:33]
	v_mfma_f32_16x16x32_bf16 v[26:29], v[134:137], v[182:185], v[26:29]
	v_mfma_f32_16x16x32_bf16 v[14:17], v[110:113], v[226:229], v[14:17]
	v_mfma_f32_16x16x32_bf16 v[10:13], v[134:137], v[226:229], v[10:13]
	v_mfma_f32_16x16x32_bf16 v[54:57], v[146:149], v[162:165], v[54:57]
	v_mfma_f32_16x16x32_bf16 v[50:53], v[154:157], v[162:165], v[50:53]
	v_mfma_f32_16x16x32_bf16 v[38:41], v[146:149], v[170:173], v[38:41]
	v_mfma_f32_16x16x32_bf16 v[34:37], v[154:157], v[170:173], v[34:37]
	v_mfma_f32_16x16x32_bf16 v[22:25], v[146:149], v[178:181], v[22:25]
	v_mfma_f32_16x16x32_bf16 v[18:21], v[154:157], v[178:181], v[18:21]
	v_mfma_f32_16x16x32_bf16 v[6:9], v[146:149], v[222:225], v[6:9]
	v_mfma_f32_16x16x32_bf16 v[2:5], v[154:157], v[222:225], v[2:5]
	v_mfma_f32_16x16x32_bf16 v[54:57], v[150:153], v[166:169], v[54:57]
	v_mfma_f32_16x16x32_bf16 v[50:53], v[158:161], v[166:169], v[50:53]
	v_mfma_f32_16x16x32_bf16 v[38:41], v[150:153], v[174:177], v[38:41]
	v_mfma_f32_16x16x32_bf16 v[34:37], v[158:161], v[174:177], v[34:37]
	v_mfma_f32_16x16x32_bf16 v[22:25], v[150:153], v[182:185], v[22:25]
	v_mfma_f32_16x16x32_bf16 v[18:21], v[158:161], v[182:185], v[18:21]
	v_mfma_f32_16x16x32_bf16 v[6:9], v[150:153], v[226:229], v[6:9]
	v_mfma_f32_16x16x32_bf16 v[2:5], v[158:161], v[226:229], v[2:5]
	s_barrier
	s_setprio 0
	s_cmp_gt_u32 s19, 41
	s_mov_b64 s[48:49], s[0:1]
	s_cbranch_scc0 .LBB0_320
	s_and_b64 vcc, exec, s[40:41]
	s_cbranch_vccz .LBB0_323
	s_barrier

.LBB0_422:
	s_add_u32 s54, s52, 0xfffc0080
	s_addc_u32 s55, s53, -1
	s_add_i32 s67, 0, 0x10000
	s_cmp_eq_u32 s66, 12
	s_cselect_b32 s57, s19, s55
	s_cselect_b32 s56, s45, s54
	v_add_u32_e32 v0, s67, v158
	s_cselect_b32 s55, s41, s65
	s_cselect_b32 s54, s51, s64
	s_add_i32 s70, 0, 0x14000
	ds_read_b128 v[142:145], v0
	ds_read_b128 v[146:149], v0 offset:1024
	ds_read_b128 v[150:153], v0 offset:2048
	ds_read_b128 v[160:163], v0 offset:3072
	v_add_u32_e32 v0, s70, v158
	ds_read_b128 v[164:167], v0
	ds_read_b128 v[168:171], v0 offset:1024
	ds_read_b128 v[172:175], v0 offset:2048
	ds_read_b128 v[176:179], v0 offset:3072
	s_add_i32 m0, s59, 0xc000
	ds_read_b128 v[180:183], v159
	ds_read_b128 v[204:207], v159 offset:1024
	ds_read_b128 v[208:211], v159 offset:2048
	ds_read_b128 v[212:215], v159 offset:3072
	ds_read_b128 v[216:219], v159 offset:4096
	ds_read_b128 v[220:223], v159 offset:5120
	ds_read_b128 v[224:227], v159 offset:6144
	ds_read_b128 v[228:231], v159 offset:7168
	global_load_lds_dwordx4 v138, s[52:53]
	s_add_i32 m0, s59, 0xe000
	s_nop 0
	global_load_lds_dwordx4 v140, s[52:53]
	s_waitcnt vmcnt(8)
	s_waitcnt lgkmcnt(0)
	s_setprio 1
	s_barrier
	v_mfma_f32_16x16x32_bf16 v[126:129], v[142:145], v[180:183], v[126:129]
	v_mfma_f32_16x16x32_bf16 v[122:125], v[150:153], v[180:183], v[122:125]
	v_mfma_f32_16x16x32_bf16 v[110:113], v[142:145], v[208:211], v[110:113]
	v_mfma_f32_16x16x32_bf16 v[106:109], v[150:153], v[208:211], v[106:109]
	v_mfma_f32_16x16x32_bf16 v[94:97], v[142:145], v[216:219], v[94:97]
	v_mfma_f32_16x16x32_bf16 v[90:93], v[150:153], v[216:219], v[90:93]
	v_mfma_f32_16x16x32_bf16 v[78:81], v[142:145], v[224:227], v[78:81]
	v_mfma_f32_16x16x32_bf16 v[74:77], v[150:153], v[224:227], v[74:77]
	v_mfma_f32_16x16x32_bf16 v[126:129], v[146:149], v[204:207], v[126:129]
	v_mfma_f32_16x16x32_bf16 v[122:125], v[160:163], v[204:207], v[122:125]
	v_mfma_f32_16x16x32_bf16 v[110:113], v[146:149], v[212:215], v[110:113]
	v_mfma_f32_16x16x32_bf16 v[106:109], v[160:163], v[212:215], v[106:109]
	v_mfma_f32_16x16x32_bf16 v[94:97], v[146:149], v[220:223], v[94:97]
	v_mfma_f32_16x16x32_bf16 v[90:93], v[160:163], v[220:223], v[90:93]
	v_mfma_f32_16x16x32_bf16 v[78:81], v[146:149], v[228:231], v[78:81]
	v_mfma_f32_16x16x32_bf16 v[74:77], v[160:163], v[228:231], v[74:77]
	v_mfma_f32_16x16x32_bf16 v[118:121], v[164:167], v[180:183], v[118:121]
	v_mfma_f32_16x16x32_bf16 v[114:117], v[172:175], v[180:183], v[114:117]
	v_mfma_f32_16x16x32_bf16 v[102:105], v[164:167], v[208:211], v[102:105]
	v_mfma_f32_16x16x32_bf16 v[98:101], v[172:175], v[208:211], v[98:101]
	v_mfma_f32_16x16x32_bf16 v[86:89], v[164:167], v[216:219], v[86:89]
	v_mfma_f32_16x16x32_bf16 v[82:85], v[172:175], v[216:219], v[82:85]
	v_mfma_f32_16x16x32_bf16 v[70:73], v[164:167], v[224:227], v[70:73]
	v_mfma_f32_16x16x32_bf16 v[66:69], v[172:175], v[224:227], v[66:69]
	v_mfma_f32_16x16x32_bf16 v[118:121], v[168:171], v[204:207], v[118:121]
	v_mfma_f32_16x16x32_bf16 v[114:117], v[176:179], v[204:207], v[114:117]
	v_mfma_f32_16x16x32_bf16 v[102:105], v[168:171], v[212:215], v[102:105]
	v_mfma_f32_16x16x32_bf16 v[98:101], v[176:179], v[212:215], v[98:101]
	v_mfma_f32_16x16x32_bf16 v[86:89], v[168:171], v[220:223], v[86:89]
	v_mfma_f32_16x16x32_bf16 v[82:85], v[176:179], v[220:223], v[82:85]
	v_mfma_f32_16x16x32_bf16 v[70:73], v[168:171], v[228:231], v[70:73]
	v_mfma_f32_16x16x32_bf16 v[66:69], v[176:179], v[228:231], v[66:69]
	s_barrier
	s_setprio 0
	s_add_i32 s67, s67, s58
	s_mov_b32 m0, s67
	ds_read_b128 v[180:183], v159 offset:16384
	ds_read_b128 v[204:207], v159 offset:17408
	ds_read_b128 v[208:211], v159 offset:18432
	ds_read_b128 v[212:215], v159 offset:19456
	ds_read_b128 v[216:219], v159 offset:20480
	ds_read_b128 v[220:223], v159 offset:21504
	ds_read_b128 v[224:227], v159 offset:22528
	ds_read_b128 v[228:231], v159 offset:23552
	global_load_lds_dwordx4 v134, s[54:55]
	s_add_i32 m0, s67, 0x2000
	s_add_u32 s68, s54, 0x40000
	s_addc_u32 s69, s55, 0
	s_add_i32 s67, s70, s58
	global_load_lds_dwordx4 v130, s[54:55]
	s_mov_b32 m0, s67
	s_nop 0
	global_load_lds_dwordx4 v134, s[68:69]
	s_add_i32 m0, s67, 0x2000
	s_nop 0
	global_load_lds_dwordx4 v130, s[68:69]
	s_mov_b32 m0, s59
	s_nop 0
	global_load_lds_dwordx4 v136, s[56:57]
	s_mov_b32 m0, s60
	s_nop 0
	global_load_lds_dwordx4 v132, s[56:57]
	s_waitcnt vmcnt(8)
	s_waitcnt lgkmcnt(0)
	s_setprio 1
	s_barrier
	v_mfma_f32_16x16x32_bf16 v[62:65], v[142:145], v[180:183], v[62:65]
	v_mfma_f32_16x16x32_bf16 v[58:61], v[150:153], v[180:183], v[58:61]
	v_mfma_f32_16x16x32_bf16 v[46:49], v[142:145], v[208:211], v[46:49]
	v_mfma_f32_16x16x32_bf16 v[42:45], v[150:153], v[208:211], v[42:45]
	v_mfma_f32_16x16x32_bf16 v[30:33], v[142:145], v[216:219], v[30:33]
	v_mfma_f32_16x16x32_bf16 v[26:29], v[150:153], v[216:219], v[26:29]
	v_mfma_f32_16x16x32_bf16 v[14:17], v[142:145], v[224:227], v[14:17]
	v_mfma_f32_16x16x32_bf16 v[10:13], v[150:153], v[224:227], v[10:13]
	v_mfma_f32_16x16x32_bf16 v[62:65], v[146:149], v[204:207], v[62:65]
	v_mfma_f32_16x16x32_bf16 v[58:61], v[160:163], v[204:207], v[58:61]
	v_mfma_f32_16x16x32_bf16 v[46:49], v[146:149], v[212:215], v[46:49]
	v_mfma_f32_16x16x32_bf16 v[42:45], v[160:163], v[212:215], v[42:45]
	v_mfma_f32_16x16x32_bf16 v[30:33], v[146:149], v[220:223], v[30:33]
	v_mfma_f32_16x16x32_bf16 v[26:29], v[160:163], v[220:223], v[26:29]
	v_mfma_f32_16x16x32_bf16 v[14:17], v[146:149], v[228:231], v[14:17]
	v_mfma_f32_16x16x32_bf16 v[10:13], v[160:163], v[228:231], v[10:13]
	v_mfma_f32_16x16x32_bf16 v[54:57], v[164:167], v[180:183], v[54:57]
	v_mfma_f32_16x16x32_bf16 v[50:53], v[172:175], v[180:183], v[50:53]
	v_mfma_f32_16x16x32_bf16 v[38:41], v[164:167], v[208:211], v[38:41]
	v_mfma_f32_16x16x32_bf16 v[34:37], v[172:175], v[208:211], v[34:37]
	v_mfma_f32_16x16x32_bf16 v[22:25], v[164:167], v[216:219], v[22:25]
	v_mfma_f32_16x16x32_bf16 v[18:21], v[172:175], v[216:219], v[18:21]
	v_mfma_f32_16x16x32_bf16 v[6:9], v[164:167], v[224:227], v[6:9]
	v_mfma_f32_16x16x32_bf16 v[2:5], v[172:175], v[224:227], v[2:5]
	v_mfma_f32_16x16x32_bf16 v[54:57], v[168:171], v[204:207], v[54:57]
	v_mfma_f32_16x16x32_bf16 v[50:53], v[176:179], v[204:207], v[50:53]
	v_mfma_f32_16x16x32_bf16 v[38:41], v[168:171], v[212:215], v[38:41]
	v_mfma_f32_16x16x32_bf16 v[34:37], v[176:179], v[212:215], v[34:37]
	v_mfma_f32_16x16x32_bf16 v[22:25], v[168:171], v[220:223], v[22:25]
	v_mfma_f32_16x16x32_bf16 v[18:21], v[176:179], v[220:223], v[18:21]
	v_mfma_f32_16x16x32_bf16 v[6:9], v[168:171], v[228:231], v[6:9]
	v_mfma_f32_16x16x32_bf16 v[2:5], v[176:179], v[228:231], v[2:5]
	s_barrier
	s_setprio 0
	s_add_i32 s67, 0, 0x18000
	v_add_u32_e32 v0, s67, v158
	s_add_i32 s68, 0, 0x1c000
	ds_read_b128 v[142:145], v0
	ds_read_b128 v[146:149], v0 offset:1024
	ds_read_b128 v[150:153], v0 offset:2048
	ds_read_b128 v[160:163], v0 offset:3072
	v_add_u32_e32 v0, s68, v158
	ds_read_b128 v[164:167], v0
	ds_read_b128 v[168:171], v0 offset:1024
	ds_read_b128 v[172:175], v0 offset:2048
	ds_read_b128 v[176:179], v0 offset:3072
	s_add_u32 s56, s56, 0x40000
	s_addc_u32 s57, s57, 0
	s_mov_b32 m0, s61
	ds_read_b128 v[180:183], v159 offset:32768
	ds_read_b128 v[204:207], v159 offset:33792
	ds_read_b128 v[208:211], v159 offset:34816
	ds_read_b128 v[212:215], v159 offset:35840
	ds_read_b128 v[216:219], v159 offset:36864
	ds_read_b128 v[220:223], v159 offset:37888
	ds_read_b128 v[224:227], v159 offset:38912
	ds_read_b128 v[228:231], v159 offset:39936
	global_load_lds_dwordx4 v136, s[56:57]
	s_mov_b32 m0, s62
	s_nop 0
	global_load_lds_dwordx4 v132, s[56:57]
	s_waitcnt vmcnt(8)
	s_waitcnt lgkmcnt(0)
	s_setprio 1
	s_barrier
	v_mfma_f32_16x16x32_bf16 v[126:129], v[142:145], v[180:183], v[126:129]
	v_mfma_f32_16x16x32_bf16 v[122:125], v[150:153], v[180:183], v[122:125]
	v_mfma_f32_16x16x32_bf16 v[110:113], v[142:145], v[208:211], v[110:113]
	v_mfma_f32_16x16x32_bf16 v[106:109], v[150:153], v[208:211], v[106:109]
	v_mfma_f32_16x16x32_bf16 v[94:97], v[142:145], v[216:219], v[94:97]
	v_mfma_f32_16x16x32_bf16 v[90:93], v[150:153], v[216:219], v[90:93]
	v_mfma_f32_16x16x32_bf16 v[78:81], v[142:145], v[224:227], v[78:81]
	v_mfma_f32_16x16x32_bf16 v[74:77], v[150:153], v[224:227], v[74:77]
	v_mfma_f32_16x16x32_bf16 v[126:129], v[146:149], v[204:207], v[126:129]
	v_mfma_f32_16x16x32_bf16 v[122:125], v[160:163], v[204:207], v[122:125]
	v_mfma_f32_16x16x32_bf16 v[110:113], v[146:149], v[212:215], v[110:113]
	v_mfma_f32_16x16x32_bf16 v[106:109], v[160:163], v[212:215], v[106:109]
	v_mfma_f32_16x16x32_bf16 v[94:97], v[146:149], v[220:223], v[94:97]
	v_mfma_f32_16x16x32_bf16 v[90:93], v[160:163], v[220:223], v[90:93]
	v_mfma_f32_16x16x32_bf16 v[78:81], v[146:149], v[228:231], v[78:81]
	v_mfma_f32_16x16x32_bf16 v[74:77], v[160:163], v[228:231], v[74:77]
	v_mfma_f32_16x16x32_bf16 v[118:121], v[164:167], v[180:183], v[118:121]
	v_mfma_f32_16x16x32_bf16 v[114:117], v[172:175], v[180:183], v[114:117]
	v_mfma_f32_16x16x32_bf16 v[102:105], v[164:167], v[208:211], v[102:105]
	v_mfma_f32_16x16x32_bf16 v[98:101], v[172:175], v[208:211], v[98:101]
	v_mfma_f32_16x16x32_bf16 v[86:89], v[164:167], v[216:219], v[86:89]
	v_mfma_f32_16x16x32_bf16 v[82:85], v[172:175], v[216:219], v[82:85]
	v_mfma_f32_16x16x32_bf16 v[70:73], v[164:167], v[224:227], v[70:73]
	v_mfma_f32_16x16x32_bf16 v[66:69], v[172:175], v[224:227], v[66:69]
	v_mfma_f32_16x16x32_bf16 v[118:121], v[168:171], v[204:207], v[118:121]
	v_mfma_f32_16x16x32_bf16 v[114:117], v[176:179], v[204:207], v[114:117]
	v_mfma_f32_16x16x32_bf16 v[102:105], v[168:171], v[212:215], v[102:105]
	v_mfma_f32_16x16x32_bf16 v[98:101], v[176:179], v[212:215], v[98:101]
	v_mfma_f32_16x16x32_bf16 v[86:89], v[168:171], v[220:223], v[86:89]
	v_mfma_f32_16x16x32_bf16 v[82:85], v[176:179], v[220:223], v[82:85]
	v_mfma_f32_16x16x32_bf16 v[70:73], v[168:171], v[228:231], v[70:73]
	v_mfma_f32_16x16x32_bf16 v[66:69], v[176:179], v[228:231], v[66:69]
	s_barrier
	s_setprio 0
	s_add_i32 s69, s67, s58
	s_add_u32 s54, s54, 0x80
	s_addc_u32 s55, s55, 0
	s_mov_b32 m0, s69
	ds_read_b128 v[180:183], v159 offset:49152
	ds_read_b128 v[204:207], v159 offset:50176
	ds_read_b128 v[208:211], v159 offset:51200
	ds_read_b128 v[212:215], v159 offset:52224
	ds_read_b128 v[216:219], v159 offset:53248
	ds_read_b128 v[220:223], v159 offset:54272
	ds_read_b128 v[224:227], v159 offset:55296
	ds_read_b128 v[228:231], v159 offset:56320
	global_load_lds_dwordx4 v134, s[54:55]
	s_add_i32 m0, s69, 0x2000
	s_add_i32 s69, s68, s58
	global_load_lds_dwordx4 v130, s[54:55]
	s_add_u32 s54, s54, 0x40000
	s_addc_u32 s55, s55, 0
	s_mov_b32 m0, s69
	s_sub_u32 s56, s56, 0x3ff80
	global_load_lds_dwordx4 v134, s[54:55]
	s_subb_u32 s57, s57, 0
	s_add_i32 m0, s69, 0x2000
	s_nop 0
	global_load_lds_dwordx4 v130, s[54:55]
	s_mov_b32 m0, s5
	s_nop 0
	global_load_lds_dwordx4 v136, s[56:57]
	s_mov_b32 m0, s6
	s_nop 0
	global_load_lds_dwordx4 v132, s[56:57]
	s_waitcnt vmcnt(8)
	s_waitcnt lgkmcnt(0)
	s_setprio 1
	s_barrier
	v_mfma_f32_16x16x32_bf16 v[62:65], v[142:145], v[180:183], v[62:65]
	v_mfma_f32_16x16x32_bf16 v[58:61], v[150:153], v[180:183], v[58:61]
	v_mfma_f32_16x16x32_bf16 v[46:49], v[142:145], v[208:211], v[46:49]
	v_mfma_f32_16x16x32_bf16 v[42:45], v[150:153], v[208:211], v[42:45]
	v_mfma_f32_16x16x32_bf16 v[30:33], v[142:145], v[216:219], v[30:33]
	v_mfma_f32_16x16x32_bf16 v[26:29], v[150:153], v[216:219], v[26:29]
	v_mfma_f32_16x16x32_bf16 v[14:17], v[142:145], v[224:227], v[14:17]
	v_mfma_f32_16x16x32_bf16 v[10:13], v[150:153], v[224:227], v[10:13]
	s_add_i32 s66, s66, 2
	s_add_u32 s52, s52, 0x100
	s_addc_u32 s53, s53, 0
	s_add_u32 s64, s64, 0x100
	s_addc_u32 s65, s65, 0
	v_mfma_f32_16x16x32_bf16 v[62:65], v[146:149], v[204:207], v[62:65]
	v_mfma_f32_16x16x32_bf16 v[58:61], v[160:163], v[204:207], v[58:61]
	v_mfma_f32_16x16x32_bf16 v[46:49], v[146:149], v[212:215], v[46:49]
	v_mfma_f32_16x16x32_bf16 v[42:45], v[160:163], v[212:215], v[42:45]
	v_mfma_f32_16x16x32_bf16 v[30:33], v[146:149], v[220:223], v[30:33]
	v_mfma_f32_16x16x32_bf16 v[26:29], v[160:163], v[220:223], v[26:29]
	v_mfma_f32_16x16x32_bf16 v[14:17], v[146:149], v[228:231], v[14:17]
	v_mfma_f32_16x16x32_bf16 v[10:13], v[160:163], v[228:231], v[10:13]
	v_mfma_f32_16x16x32_bf16 v[54:57], v[164:167], v[180:183], v[54:57]
	v_mfma_f32_16x16x32_bf16 v[50:53], v[172:175], v[180:183], v[50:53]
	v_mfma_f32_16x16x32_bf16 v[38:41], v[164:167], v[208:211], v[38:41]
	v_mfma_f32_16x16x32_bf16 v[34:37], v[172:175], v[208:211], v[34:37]
	v_mfma_f32_16x16x32_bf16 v[22:25], v[164:167], v[216:219], v[22:25]
	v_mfma_f32_16x16x32_bf16 v[18:21], v[172:175], v[216:219], v[18:21]
	v_mfma_f32_16x16x32_bf16 v[6:9], v[164:167], v[224:227], v[6:9]
	v_mfma_f32_16x16x32_bf16 v[2:5], v[172:175], v[224:227], v[2:5]
	v_mfma_f32_16x16x32_bf16 v[54:57], v[168:171], v[204:207], v[54:57]
	v_mfma_f32_16x16x32_bf16 v[50:53], v[176:179], v[204:207], v[50:53]
	v_mfma_f32_16x16x32_bf16 v[38:41], v[168:171], v[212:215], v[38:41]
	v_mfma_f32_16x16x32_bf16 v[34:37], v[176:179], v[212:215], v[34:37]
	v_mfma_f32_16x16x32_bf16 v[22:25], v[168:171], v[220:223], v[22:25]
	v_mfma_f32_16x16x32_bf16 v[18:21], v[176:179], v[220:223], v[18:21]
	v_mfma_f32_16x16x32_bf16 v[6:9], v[168:171], v[228:231], v[6:9]
	v_mfma_f32_16x16x32_bf16 v[2:5], v[176:179], v[228:231], v[2:5]
	s_barrier
	s_setprio 0
	s_cmp_gt_u32 s66, 13
	s_cbranch_scc0 .LBB0_422
	s_and_b64 vcc, exec, s[38:39]
	s_cbranch_vccz .LBB0_425
	s_barrier

.LBB0_479:
	s_add_u32 s54, s52, 0xfffc0080
	s_addc_u32 s55, s53, -1
	s_add_i32 s61, 0, 0x10000
	s_cmp_eq_u32 s60, 12
	s_cselect_b32 s57, s19, s55
	s_cselect_b32 s56, s45, s54
	v_add_u32_e32 v0, s61, v160
	s_cselect_b32 s55, s41, s59
	s_cselect_b32 s54, s47, s58
	s_add_i32 s64, 0, 0x14000
	ds_read_b128 v[142:145], v0
	ds_read_b128 v[146:149], v0 offset:1024
	ds_read_b128 v[150:153], v0 offset:2048
	ds_read_b128 v[154:157], v0 offset:3072
	v_add_u32_e32 v0, s64, v160
	ds_read_b128 v[162:165], v0
	ds_read_b128 v[166:169], v0 offset:1024
	ds_read_b128 v[170:173], v0 offset:2048
	ds_read_b128 v[174:177], v0 offset:3072
	s_add_i32 m0, s71, 0xc000
	ds_read_b128 v[178:181], v161
	ds_read_b128 v[182:185], v161 offset:1024
	ds_read_b128 v[204:207], v161 offset:2048
	ds_read_b128 v[208:211], v161 offset:3072
	ds_read_b128 v[212:215], v161 offset:4096
	ds_read_b128 v[216:219], v161 offset:5120
	ds_read_b128 v[220:223], v161 offset:6144
	ds_read_b128 v[224:227], v161 offset:7168
	global_load_lds_dwordx4 v138, s[52:53]
	s_add_i32 m0, s71, 0xe000
	s_nop 0
	global_load_lds_dwordx4 v140, s[52:53]
	s_waitcnt vmcnt(8)
	s_waitcnt lgkmcnt(0)
	s_setprio 1
	s_barrier
	v_mfma_f32_16x16x32_bf16 v[126:129], v[142:145], v[178:181], v[126:129]
	v_mfma_f32_16x16x32_bf16 v[122:125], v[150:153], v[178:181], v[122:125]
	v_mfma_f32_16x16x32_bf16 v[110:113], v[142:145], v[204:207], v[110:113]
	v_mfma_f32_16x16x32_bf16 v[106:109], v[150:153], v[204:207], v[106:109]
	v_mfma_f32_16x16x32_bf16 v[94:97], v[142:145], v[212:215], v[94:97]
	v_mfma_f32_16x16x32_bf16 v[90:93], v[150:153], v[212:215], v[90:93]
	v_mfma_f32_16x16x32_bf16 v[78:81], v[142:145], v[220:223], v[78:81]
	v_mfma_f32_16x16x32_bf16 v[74:77], v[150:153], v[220:223], v[74:77]
	v_mfma_f32_16x16x32_bf16 v[126:129], v[146:149], v[182:185], v[126:129]
	v_mfma_f32_16x16x32_bf16 v[122:125], v[154:157], v[182:185], v[122:125]
	v_mfma_f32_16x16x32_bf16 v[110:113], v[146:149], v[208:211], v[110:113]
	v_mfma_f32_16x16x32_bf16 v[106:109], v[154:157], v[208:211], v[106:109]
	v_mfma_f32_16x16x32_bf16 v[94:97], v[146:149], v[216:219], v[94:97]
	v_mfma_f32_16x16x32_bf16 v[90:93], v[154:157], v[216:219], v[90:93]
	v_mfma_f32_16x16x32_bf16 v[78:81], v[146:149], v[224:227], v[78:81]
	v_mfma_f32_16x16x32_bf16 v[74:77], v[154:157], v[224:227], v[74:77]
	v_mfma_f32_16x16x32_bf16 v[118:121], v[162:165], v[178:181], v[118:121]
	v_mfma_f32_16x16x32_bf16 v[114:117], v[170:173], v[178:181], v[114:117]
	v_mfma_f32_16x16x32_bf16 v[102:105], v[162:165], v[204:207], v[102:105]
	v_mfma_f32_16x16x32_bf16 v[98:101], v[170:173], v[204:207], v[98:101]
	v_mfma_f32_16x16x32_bf16 v[86:89], v[162:165], v[212:215], v[86:89]
	v_mfma_f32_16x16x32_bf16 v[82:85], v[170:173], v[212:215], v[82:85]
	v_mfma_f32_16x16x32_bf16 v[70:73], v[162:165], v[220:223], v[70:73]
	v_mfma_f32_16x16x32_bf16 v[66:69], v[170:173], v[220:223], v[66:69]
	v_mfma_f32_16x16x32_bf16 v[118:121], v[166:169], v[182:185], v[118:121]
	v_mfma_f32_16x16x32_bf16 v[114:117], v[174:177], v[182:185], v[114:117]
	v_mfma_f32_16x16x32_bf16 v[102:105], v[166:169], v[208:211], v[102:105]
	v_mfma_f32_16x16x32_bf16 v[98:101], v[174:177], v[208:211], v[98:101]
	v_mfma_f32_16x16x32_bf16 v[86:89], v[166:169], v[216:219], v[86:89]
	v_mfma_f32_16x16x32_bf16 v[82:85], v[174:177], v[216:219], v[82:85]
	v_mfma_f32_16x16x32_bf16 v[70:73], v[166:169], v[224:227], v[70:73]
	v_mfma_f32_16x16x32_bf16 v[66:69], v[174:177], v[224:227], v[66:69]
	s_barrier
	s_setprio 0
	s_add_i32 s61, s61, s70
	s_mov_b32 m0, s61
	ds_read_b128 v[178:181], v161 offset:16384
	ds_read_b128 v[182:185], v161 offset:17408
	ds_read_b128 v[204:207], v161 offset:18432
	ds_read_b128 v[208:211], v161 offset:19456
	ds_read_b128 v[212:215], v161 offset:20480
	ds_read_b128 v[216:219], v161 offset:21504
	ds_read_b128 v[220:223], v161 offset:22528
	ds_read_b128 v[224:227], v161 offset:23552
	global_load_lds_dwordx4 v134, s[54:55]
	s_add_i32 m0, s61, 0x2000
	s_add_u32 s62, s54, 0x40000
	s_addc_u32 s63, s55, 0
	s_add_i32 s61, s64, s70
	global_load_lds_dwordx4 v130, s[54:55]
	s_mov_b32 m0, s61
	s_nop 0
	global_load_lds_dwordx4 v134, s[62:63]
	s_add_i32 m0, s61, 0x2000
	s_nop 0
	global_load_lds_dwordx4 v130, s[62:63]
	s_mov_b32 m0, s71
	s_nop 0
	global_load_lds_dwordx4 v136, s[56:57]
	s_mov_b32 m0, s72
	s_nop 0
	global_load_lds_dwordx4 v132, s[56:57]
	s_waitcnt vmcnt(8)
	s_waitcnt lgkmcnt(0)
	s_setprio 1
	s_barrier
	v_mfma_f32_16x16x32_bf16 v[62:65], v[142:145], v[178:181], v[62:65]
	v_mfma_f32_16x16x32_bf16 v[58:61], v[150:153], v[178:181], v[58:61]
	v_mfma_f32_16x16x32_bf16 v[46:49], v[142:145], v[204:207], v[46:49]
	v_mfma_f32_16x16x32_bf16 v[42:45], v[150:153], v[204:207], v[42:45]
	v_mfma_f32_16x16x32_bf16 v[30:33], v[142:145], v[212:215], v[30:33]
	v_mfma_f32_16x16x32_bf16 v[26:29], v[150:153], v[212:215], v[26:29]
	v_mfma_f32_16x16x32_bf16 v[14:17], v[142:145], v[220:223], v[14:17]
	v_mfma_f32_16x16x32_bf16 v[10:13], v[150:153], v[220:223], v[10:13]
	v_mfma_f32_16x16x32_bf16 v[62:65], v[146:149], v[182:185], v[62:65]
	v_mfma_f32_16x16x32_bf16 v[58:61], v[154:157], v[182:185], v[58:61]
	v_mfma_f32_16x16x32_bf16 v[46:49], v[146:149], v[208:211], v[46:49]
	v_mfma_f32_16x16x32_bf16 v[42:45], v[154:157], v[208:211], v[42:45]
	v_mfma_f32_16x16x32_bf16 v[30:33], v[146:149], v[216:219], v[30:33]
	v_mfma_f32_16x16x32_bf16 v[26:29], v[154:157], v[216:219], v[26:29]
	v_mfma_f32_16x16x32_bf16 v[14:17], v[146:149], v[224:227], v[14:17]
	v_mfma_f32_16x16x32_bf16 v[10:13], v[154:157], v[224:227], v[10:13]
	v_mfma_f32_16x16x32_bf16 v[54:57], v[162:165], v[178:181], v[54:57]
	v_mfma_f32_16x16x32_bf16 v[50:53], v[170:173], v[178:181], v[50:53]
	v_mfma_f32_16x16x32_bf16 v[38:41], v[162:165], v[204:207], v[38:41]
	v_mfma_f32_16x16x32_bf16 v[34:37], v[170:173], v[204:207], v[34:37]
	v_mfma_f32_16x16x32_bf16 v[22:25], v[162:165], v[212:215], v[22:25]
	v_mfma_f32_16x16x32_bf16 v[18:21], v[170:173], v[212:215], v[18:21]
	v_mfma_f32_16x16x32_bf16 v[6:9], v[162:165], v[220:223], v[6:9]
	v_mfma_f32_16x16x32_bf16 v[2:5], v[170:173], v[220:223], v[2:5]
	v_mfma_f32_16x16x32_bf16 v[54:57], v[166:169], v[182:185], v[54:57]
	v_mfma_f32_16x16x32_bf16 v[50:53], v[174:177], v[182:185], v[50:53]
	v_mfma_f32_16x16x32_bf16 v[38:41], v[166:169], v[208:211], v[38:41]
	v_mfma_f32_16x16x32_bf16 v[34:37], v[174:177], v[208:211], v[34:37]
	v_mfma_f32_16x16x32_bf16 v[22:25], v[166:169], v[216:219], v[22:25]
	v_mfma_f32_16x16x32_bf16 v[18:21], v[174:177], v[216:219], v[18:21]
	v_mfma_f32_16x16x32_bf16 v[6:9], v[166:169], v[224:227], v[6:9]
	v_mfma_f32_16x16x32_bf16 v[2:5], v[174:177], v[224:227], v[2:5]
	s_barrier
	s_setprio 0
	s_add_i32 s61, 0, 0x18000
	v_add_u32_e32 v0, s61, v160
	s_add_i32 s62, 0, 0x1c000
	ds_read_b128 v[142:145], v0
	ds_read_b128 v[146:149], v0 offset:1024
	ds_read_b128 v[150:153], v0 offset:2048
	ds_read_b128 v[154:157], v0 offset:3072
	v_add_u32_e32 v0, s62, v160
	ds_read_b128 v[162:165], v0
	ds_read_b128 v[166:169], v0 offset:1024
	ds_read_b128 v[170:173], v0 offset:2048
	ds_read_b128 v[174:177], v0 offset:3072
	s_add_u32 s56, s56, 0x40000
	s_addc_u32 s57, s57, 0
	s_mov_b32 m0, s73
	ds_read_b128 v[178:181], v161 offset:32768
	ds_read_b128 v[182:185], v161 offset:33792
	ds_read_b128 v[204:207], v161 offset:34816
	ds_read_b128 v[208:211], v161 offset:35840
	ds_read_b128 v[212:215], v161 offset:36864
	ds_read_b128 v[216:219], v161 offset:37888
	ds_read_b128 v[220:223], v161 offset:38912
	ds_read_b128 v[224:227], v161 offset:39936
	global_load_lds_dwordx4 v136, s[56:57]
	s_mov_b32 m0, s74
	s_nop 0
	global_load_lds_dwordx4 v132, s[56:57]
	s_waitcnt vmcnt(8)
	s_waitcnt lgkmcnt(0)
	s_setprio 1
	s_barrier
	v_mfma_f32_16x16x32_bf16 v[126:129], v[142:145], v[178:181], v[126:129]
	v_mfma_f32_16x16x32_bf16 v[122:125], v[150:153], v[178:181], v[122:125]
	v_mfma_f32_16x16x32_bf16 v[110:113], v[142:145], v[204:207], v[110:113]
	v_mfma_f32_16x16x32_bf16 v[106:109], v[150:153], v[204:207], v[106:109]
	v_mfma_f32_16x16x32_bf16 v[94:97], v[142:145], v[212:215], v[94:97]
	v_mfma_f32_16x16x32_bf16 v[90:93], v[150:153], v[212:215], v[90:93]
	v_mfma_f32_16x16x32_bf16 v[78:81], v[142:145], v[220:223], v[78:81]
	v_mfma_f32_16x16x32_bf16 v[74:77], v[150:153], v[220:223], v[74:77]
	v_mfma_f32_16x16x32_bf16 v[126:129], v[146:149], v[182:185], v[126:129]
	v_mfma_f32_16x16x32_bf16 v[122:125], v[154:157], v[182:185], v[122:125]
	v_mfma_f32_16x16x32_bf16 v[110:113], v[146:149], v[208:211], v[110:113]
	v_mfma_f32_16x16x32_bf16 v[106:109], v[154:157], v[208:211], v[106:109]
	v_mfma_f32_16x16x32_bf16 v[94:97], v[146:149], v[216:219], v[94:97]
	v_mfma_f32_16x16x32_bf16 v[90:93], v[154:157], v[216:219], v[90:93]
	v_mfma_f32_16x16x32_bf16 v[78:81], v[146:149], v[224:227], v[78:81]
	v_mfma_f32_16x16x32_bf16 v[74:77], v[154:157], v[224:227], v[74:77]
	v_mfma_f32_16x16x32_bf16 v[118:121], v[162:165], v[178:181], v[118:121]
	v_mfma_f32_16x16x32_bf16 v[114:117], v[170:173], v[178:181], v[114:117]
	v_mfma_f32_16x16x32_bf16 v[102:105], v[162:165], v[204:207], v[102:105]
	v_mfma_f32_16x16x32_bf16 v[98:101], v[170:173], v[204:207], v[98:101]
	v_mfma_f32_16x16x32_bf16 v[86:89], v[162:165], v[212:215], v[86:89]
	v_mfma_f32_16x16x32_bf16 v[82:85], v[170:173], v[212:215], v[82:85]
	v_mfma_f32_16x16x32_bf16 v[70:73], v[162:165], v[220:223], v[70:73]
	v_mfma_f32_16x16x32_bf16 v[66:69], v[170:173], v[220:223], v[66:69]
	v_mfma_f32_16x16x32_bf16 v[118:121], v[166:169], v[182:185], v[118:121]
	v_mfma_f32_16x16x32_bf16 v[114:117], v[174:177], v[182:185], v[114:117]
	v_mfma_f32_16x16x32_bf16 v[102:105], v[166:169], v[208:211], v[102:105]
	v_mfma_f32_16x16x32_bf16 v[98:101], v[174:177], v[208:211], v[98:101]
	v_mfma_f32_16x16x32_bf16 v[86:89], v[166:169], v[216:219], v[86:89]
	v_mfma_f32_16x16x32_bf16 v[82:85], v[174:177], v[216:219], v[82:85]
	v_mfma_f32_16x16x32_bf16 v[70:73], v[166:169], v[224:227], v[70:73]
	v_mfma_f32_16x16x32_bf16 v[66:69], v[174:177], v[224:227], v[66:69]
	s_barrier
	s_setprio 0
	s_add_i32 s63, s61, s70
	s_add_u32 s54, s54, 0x80
	s_addc_u32 s55, s55, 0
	s_mov_b32 m0, s63
	ds_read_b128 v[178:181], v161 offset:49152
	ds_read_b128 v[182:185], v161 offset:50176
	ds_read_b128 v[204:207], v161 offset:51200
	ds_read_b128 v[208:211], v161 offset:52224
	ds_read_b128 v[212:215], v161 offset:53248
	ds_read_b128 v[216:219], v161 offset:54272
	ds_read_b128 v[220:223], v161 offset:55296
	ds_read_b128 v[224:227], v161 offset:56320
	global_load_lds_dwordx4 v134, s[54:55]
	s_add_i32 m0, s63, 0x2000
	s_add_i32 s63, s62, s70
	global_load_lds_dwordx4 v130, s[54:55]
	s_add_u32 s54, s54, 0x40000
	s_addc_u32 s55, s55, 0
	s_mov_b32 m0, s63
	s_sub_u32 s56, s56, 0x3ff80
	global_load_lds_dwordx4 v134, s[54:55]
	s_subb_u32 s57, s57, 0
	s_add_i32 m0, s63, 0x2000
	s_nop 0
	global_load_lds_dwordx4 v130, s[54:55]
	s_mov_b32 m0, s86
	s_nop 0
	global_load_lds_dwordx4 v136, s[56:57]
	s_mov_b32 m0, s87
	s_nop 0
	global_load_lds_dwordx4 v132, s[56:57]
	s_waitcnt vmcnt(8)
	s_waitcnt lgkmcnt(0)
	s_setprio 1
	s_barrier
	v_mfma_f32_16x16x32_bf16 v[62:65], v[142:145], v[178:181], v[62:65]
	v_mfma_f32_16x16x32_bf16 v[58:61], v[150:153], v[178:181], v[58:61]
	v_mfma_f32_16x16x32_bf16 v[46:49], v[142:145], v[204:207], v[46:49]
	v_mfma_f32_16x16x32_bf16 v[42:45], v[150:153], v[204:207], v[42:45]
	v_mfma_f32_16x16x32_bf16 v[30:33], v[142:145], v[212:215], v[30:33]
	v_mfma_f32_16x16x32_bf16 v[26:29], v[150:153], v[212:215], v[26:29]
	v_mfma_f32_16x16x32_bf16 v[14:17], v[142:145], v[220:223], v[14:17]
	v_mfma_f32_16x16x32_bf16 v[10:13], v[150:153], v[220:223], v[10:13]
	s_add_i32 s60, s60, 2
	s_add_u32 s52, s52, 0x100
	s_addc_u32 s53, s53, 0
	s_add_u32 s58, s58, 0x100
	s_addc_u32 s59, s59, 0
	v_mfma_f32_16x16x32_bf16 v[62:65], v[146:149], v[182:185], v[62:65]
	v_mfma_f32_16x16x32_bf16 v[58:61], v[154:157], v[182:185], v[58:61]
	v_mfma_f32_16x16x32_bf16 v[46:49], v[146:149], v[208:211], v[46:49]
	v_mfma_f32_16x16x32_bf16 v[42:45], v[154:157], v[208:211], v[42:45]
	v_mfma_f32_16x16x32_bf16 v[30:33], v[146:149], v[216:219], v[30:33]
	v_mfma_f32_16x16x32_bf16 v[26:29], v[154:157], v[216:219], v[26:29]
	v_mfma_f32_16x16x32_bf16 v[14:17], v[146:149], v[224:227], v[14:17]
	v_mfma_f32_16x16x32_bf16 v[10:13], v[154:157], v[224:227], v[10:13]
	v_mfma_f32_16x16x32_bf16 v[54:57], v[162:165], v[178:181], v[54:57]
	v_mfma_f32_16x16x32_bf16 v[50:53], v[170:173], v[178:181], v[50:53]
	v_mfma_f32_16x16x32_bf16 v[38:41], v[162:165], v[204:207], v[38:41]
	v_mfma_f32_16x16x32_bf16 v[34:37], v[170:173], v[204:207], v[34:37]
	v_mfma_f32_16x16x32_bf16 v[22:25], v[162:165], v[212:215], v[22:25]
	v_mfma_f32_16x16x32_bf16 v[18:21], v[170:173], v[212:215], v[18:21]
	v_mfma_f32_16x16x32_bf16 v[6:9], v[162:165], v[220:223], v[6:9]
	v_mfma_f32_16x16x32_bf16 v[2:5], v[170:173], v[220:223], v[2:5]
	v_mfma_f32_16x16x32_bf16 v[54:57], v[166:169], v[182:185], v[54:57]
	v_mfma_f32_16x16x32_bf16 v[50:53], v[174:177], v[182:185], v[50:53]
	v_mfma_f32_16x16x32_bf16 v[38:41], v[166:169], v[208:211], v[38:41]
	v_mfma_f32_16x16x32_bf16 v[34:37], v[174:177], v[208:211], v[34:37]
	v_mfma_f32_16x16x32_bf16 v[22:25], v[166:169], v[216:219], v[22:25]
	v_mfma_f32_16x16x32_bf16 v[18:21], v[174:177], v[216:219], v[18:21]
	v_mfma_f32_16x16x32_bf16 v[6:9], v[166:169], v[224:227], v[6:9]
	v_mfma_f32_16x16x32_bf16 v[2:5], v[174:177], v[224:227], v[2:5]
	s_barrier
	s_setprio 0
	s_cmp_gt_u32 s60, 13
	s_cbranch_scc0 .LBB0_479
	s_and_b64 vcc, exec, s[38:39]
	s_cbranch_vccz .LBB0_482
	s_barrier

.LBB0_900:
	s_add_u32 s47, s52, 0xfffc0080
	s_addc_u32 s54, s53, -1
	s_add_i32 s68, 0, 0x10000
	s_cmp_eq_u32 s45, 12
	s_cselect_b32 s57, s1, s54
	s_cselect_b32 s56, s5, s47
	v_add_u32_e32 v0, s68, v221
	s_cselect_b32 s55, s6, s19
	s_cselect_b32 s54, s7, s18
	s_add_i32 s47, 0, 0x14000
	ds_read_b128 v[106:109], v0
	ds_read_b128 v[110:113], v0 offset:1024
	ds_read_b128 v[126:129], v0 offset:2048
	ds_read_b128 v[134:137], v0 offset:3072
	v_add_u32_e32 v0, s47, v221
	ds_read_b128 v[146:149], v0
	ds_read_b128 v[150:153], v0 offset:1024
	ds_read_b128 v[154:157], v0 offset:2048
	ds_read_b128 v[158:161], v0 offset:3072
	v_lshl_add_u64 v[216:217], s[52:53], 0, v[212:213]
	s_add_i32 m0, s59, 0xc000
	ds_read_b128 v[162:165], v222
	ds_read_b128 v[166:169], v222 offset:1024
	ds_read_b128 v[170:173], v222 offset:2048
	ds_read_b128 v[174:177], v222 offset:3072
	ds_read_b128 v[178:181], v222 offset:4096
	ds_read_b128 v[182:185], v222 offset:5120
	ds_read_b128 v[224:227], v222 offset:6144
	ds_read_b128 v[228:231], v222 offset:7168
	global_load_lds_dwordx4 v[216:217], off
	v_lshl_add_u64 v[216:217], s[52:53], 0, v[214:215]
	s_add_i32 m0, s59, 0xe000
	s_nop 0
	global_load_lds_dwordx4 v[216:217], off
	s_waitcnt vmcnt(8)
	s_waitcnt lgkmcnt(0)
	s_setprio 1
	s_barrier
	v_mfma_f32_16x16x32_bf16 v[142:145], v[106:109], v[162:165], v[142:145]
	v_mfma_f32_16x16x32_bf16 v[138:141], v[126:129], v[162:165], v[138:141]
	v_mfma_f32_16x16x32_bf16 v[118:121], v[106:109], v[170:173], v[118:121]
	v_mfma_f32_16x16x32_bf16 v[114:117], v[126:129], v[170:173], v[114:117]
	v_mfma_f32_16x16x32_bf16 v[94:97], v[106:109], v[178:181], v[94:97]
	v_mfma_f32_16x16x32_bf16 v[90:93], v[126:129], v[178:181], v[90:93]
	v_mfma_f32_16x16x32_bf16 v[78:81], v[106:109], v[224:227], v[78:81]
	v_mfma_f32_16x16x32_bf16 v[74:77], v[126:129], v[224:227], v[74:77]
	v_mfma_f32_16x16x32_bf16 v[142:145], v[110:113], v[166:169], v[142:145]
	v_mfma_f32_16x16x32_bf16 v[138:141], v[134:137], v[166:169], v[138:141]
	v_mfma_f32_16x16x32_bf16 v[118:121], v[110:113], v[174:177], v[118:121]
	v_mfma_f32_16x16x32_bf16 v[114:117], v[134:137], v[174:177], v[114:117]
	v_mfma_f32_16x16x32_bf16 v[94:97], v[110:113], v[182:185], v[94:97]
	v_mfma_f32_16x16x32_bf16 v[90:93], v[134:137], v[182:185], v[90:93]
	v_mfma_f32_16x16x32_bf16 v[78:81], v[110:113], v[228:231], v[78:81]
	v_mfma_f32_16x16x32_bf16 v[74:77], v[134:137], v[228:231], v[74:77]
	v_mfma_f32_16x16x32_bf16 v[130:133], v[146:149], v[162:165], v[130:133]
	v_mfma_f32_16x16x32_bf16 v[122:125], v[154:157], v[162:165], v[122:125]
	v_mfma_f32_16x16x32_bf16 v[102:105], v[146:149], v[170:173], v[102:105]
	v_mfma_f32_16x16x32_bf16 v[98:101], v[154:157], v[170:173], v[98:101]
	v_mfma_f32_16x16x32_bf16 v[86:89], v[146:149], v[178:181], v[86:89]
	v_mfma_f32_16x16x32_bf16 v[82:85], v[154:157], v[178:181], v[82:85]
	v_mfma_f32_16x16x32_bf16 v[70:73], v[146:149], v[224:227], v[70:73]
	v_mfma_f32_16x16x32_bf16 v[66:69], v[154:157], v[224:227], v[66:69]
	v_mfma_f32_16x16x32_bf16 v[130:133], v[150:153], v[166:169], v[130:133]
	v_mfma_f32_16x16x32_bf16 v[122:125], v[158:161], v[166:169], v[122:125]
	v_mfma_f32_16x16x32_bf16 v[102:105], v[150:153], v[174:177], v[102:105]
	v_mfma_f32_16x16x32_bf16 v[98:101], v[158:161], v[174:177], v[98:101]
	v_mfma_f32_16x16x32_bf16 v[86:89], v[150:153], v[182:185], v[86:89]
	v_mfma_f32_16x16x32_bf16 v[82:85], v[158:161], v[182:185], v[82:85]
	v_mfma_f32_16x16x32_bf16 v[70:73], v[150:153], v[228:231], v[70:73]
	v_mfma_f32_16x16x32_bf16 v[66:69], v[158:161], v[228:231], v[66:69]
	s_barrier
	s_setprio 0
	s_add_i32 s68, s68, s58
	v_lshl_add_u64 v[216:217], s[54:55], 0, v[208:209]
	s_mov_b32 m0, s68
	ds_read_b128 v[162:165], v222 offset:16384
	ds_read_b128 v[166:169], v222 offset:17408
	ds_read_b128 v[170:173], v222 offset:18432
	ds_read_b128 v[174:177], v222 offset:19456
	ds_read_b128 v[178:181], v222 offset:20480
	ds_read_b128 v[182:185], v222 offset:21504
	ds_read_b128 v[224:227], v222 offset:22528
	ds_read_b128 v[228:231], v222 offset:23552
	global_load_lds_dwordx4 v[216:217], off
	s_add_i32 m0, s68, 0x2000
	s_add_u32 s68, s54, 0x40000
	v_lshl_add_u64 v[240:241], s[54:55], 0, v[204:205]
	s_addc_u32 s69, s55, 0
	s_add_i32 s47, s47, s58
	global_load_lds_dwordx4 v[240:241], off
	v_lshl_add_u64 v[242:243], s[68:69], 0, v[208:209]
	s_mov_b32 m0, s47
	v_lshl_add_u64 v[244:245], s[56:57], 0, v[206:207]
	global_load_lds_dwordx4 v[242:243], off
	v_lshl_add_u64 v[242:243], s[68:69], 0, v[204:205]
	s_add_i32 m0, s47, 0x2000
	s_nop 0
	global_load_lds_dwordx4 v[242:243], off
	v_lshl_add_u64 v[242:243], s[56:57], 0, v[210:211]
	s_mov_b32 m0, s59
	s_nop 0
	global_load_lds_dwordx4 v[242:243], off
	s_mov_b32 m0, s60
	s_nop 0
	global_load_lds_dwordx4 v[244:245], off
	s_waitcnt vmcnt(8)
	s_waitcnt lgkmcnt(0)
	s_setprio 1
	s_barrier
	v_mfma_f32_16x16x32_bf16 v[62:65], v[106:109], v[162:165], v[62:65]
	v_mfma_f32_16x16x32_bf16 v[58:61], v[126:129], v[162:165], v[58:61]
	v_mfma_f32_16x16x32_bf16 v[46:49], v[106:109], v[170:173], v[46:49]
	v_mfma_f32_16x16x32_bf16 v[42:45], v[126:129], v[170:173], v[42:45]
	v_mfma_f32_16x16x32_bf16 v[30:33], v[106:109], v[178:181], v[30:33]
	v_mfma_f32_16x16x32_bf16 v[26:29], v[126:129], v[178:181], v[26:29]
	v_mfma_f32_16x16x32_bf16 v[14:17], v[106:109], v[224:227], v[14:17]
	v_mfma_f32_16x16x32_bf16 v[10:13], v[126:129], v[224:227], v[10:13]
	v_mfma_f32_16x16x32_bf16 v[62:65], v[110:113], v[166:169], v[62:65]
	v_mfma_f32_16x16x32_bf16 v[58:61], v[134:137], v[166:169], v[58:61]
	v_mfma_f32_16x16x32_bf16 v[46:49], v[110:113], v[174:177], v[46:49]
	v_mfma_f32_16x16x32_bf16 v[42:45], v[134:137], v[174:177], v[42:45]
	v_mfma_f32_16x16x32_bf16 v[30:33], v[110:113], v[182:185], v[30:33]
	v_mfma_f32_16x16x32_bf16 v[26:29], v[134:137], v[182:185], v[26:29]
	v_mfma_f32_16x16x32_bf16 v[14:17], v[110:113], v[228:231], v[14:17]
	v_mfma_f32_16x16x32_bf16 v[10:13], v[134:137], v[228:231], v[10:13]
	v_mfma_f32_16x16x32_bf16 v[54:57], v[146:149], v[162:165], v[54:57]
	v_mfma_f32_16x16x32_bf16 v[50:53], v[154:157], v[162:165], v[50:53]
	v_mfma_f32_16x16x32_bf16 v[38:41], v[146:149], v[170:173], v[38:41]
	v_mfma_f32_16x16x32_bf16 v[34:37], v[154:157], v[170:173], v[34:37]
	v_mfma_f32_16x16x32_bf16 v[22:25], v[146:149], v[178:181], v[22:25]
	v_mfma_f32_16x16x32_bf16 v[18:21], v[154:157], v[178:181], v[18:21]
	v_mfma_f32_16x16x32_bf16 v[6:9], v[146:149], v[224:227], v[6:9]
	v_mfma_f32_16x16x32_bf16 v[2:5], v[154:157], v[224:227], v[2:5]
	v_mfma_f32_16x16x32_bf16 v[54:57], v[150:153], v[166:169], v[54:57]
	v_mfma_f32_16x16x32_bf16 v[50:53], v[158:161], v[166:169], v[50:53]
	v_mfma_f32_16x16x32_bf16 v[38:41], v[150:153], v[174:177], v[38:41]
	v_mfma_f32_16x16x32_bf16 v[34:37], v[158:161], v[174:177], v[34:37]
	v_mfma_f32_16x16x32_bf16 v[22:25], v[150:153], v[182:185], v[22:25]
	v_mfma_f32_16x16x32_bf16 v[18:21], v[158:161], v[182:185], v[18:21]
	v_mfma_f32_16x16x32_bf16 v[6:9], v[150:153], v[228:231], v[6:9]
	v_mfma_f32_16x16x32_bf16 v[2:5], v[158:161], v[228:231], v[2:5]
	s_barrier
	s_setprio 0
	s_add_i32 s47, 0, 0x18000
	v_add_u32_e32 v0, s47, v221
	s_add_i32 s68, 0, 0x1c000
	ds_read_b128 v[106:109], v0
	ds_read_b128 v[110:113], v0 offset:1024
	ds_read_b128 v[126:129], v0 offset:2048
	ds_read_b128 v[134:137], v0 offset:3072
	v_add_u32_e32 v0, s68, v221
	ds_read_b128 v[146:149], v0
	ds_read_b128 v[150:153], v0 offset:1024
	ds_read_b128 v[154:157], v0 offset:2048
	ds_read_b128 v[158:161], v0 offset:3072
	s_add_u32 s56, s56, 0x40000
	s_addc_u32 s57, s57, 0
	s_mov_b32 m0, s61
	v_lshl_add_u64 v[246:247], s[56:57], 0, v[210:211]
	ds_read_b128 v[162:165], v222 offset:32768
	ds_read_b128 v[166:169], v222 offset:33792
	ds_read_b128 v[170:173], v222 offset:34816
	ds_read_b128 v[174:177], v222 offset:35840
	ds_read_b128 v[178:181], v222 offset:36864
	ds_read_b128 v[182:185], v222 offset:37888
	ds_read_b128 v[224:227], v222 offset:38912
	ds_read_b128 v[228:231], v222 offset:39936
	global_load_lds_dwordx4 v[246:247], off
	v_lshl_add_u64 v[246:247], s[56:57], 0, v[206:207]
	s_mov_b32 m0, s62
	s_nop 0
	global_load_lds_dwordx4 v[246:247], off
	s_waitcnt vmcnt(8)
	s_waitcnt lgkmcnt(0)
	s_setprio 1
	s_barrier
	v_mfma_f32_16x16x32_bf16 v[142:145], v[106:109], v[162:165], v[142:145]
	v_mfma_f32_16x16x32_bf16 v[138:141], v[126:129], v[162:165], v[138:141]
	v_mfma_f32_16x16x32_bf16 v[118:121], v[106:109], v[170:173], v[118:121]
	v_mfma_f32_16x16x32_bf16 v[114:117], v[126:129], v[170:173], v[114:117]
	v_mfma_f32_16x16x32_bf16 v[94:97], v[106:109], v[178:181], v[94:97]
	v_mfma_f32_16x16x32_bf16 v[90:93], v[126:129], v[178:181], v[90:93]
	v_mfma_f32_16x16x32_bf16 v[78:81], v[106:109], v[224:227], v[78:81]
	v_mfma_f32_16x16x32_bf16 v[74:77], v[126:129], v[224:227], v[74:77]
	v_mfma_f32_16x16x32_bf16 v[142:145], v[110:113], v[166:169], v[142:145]
	v_mfma_f32_16x16x32_bf16 v[138:141], v[134:137], v[166:169], v[138:141]
	v_mfma_f32_16x16x32_bf16 v[118:121], v[110:113], v[174:177], v[118:121]
	v_mfma_f32_16x16x32_bf16 v[114:117], v[134:137], v[174:177], v[114:117]
	v_mfma_f32_16x16x32_bf16 v[94:97], v[110:113], v[182:185], v[94:97]
	v_mfma_f32_16x16x32_bf16 v[90:93], v[134:137], v[182:185], v[90:93]
	v_mfma_f32_16x16x32_bf16 v[78:81], v[110:113], v[228:231], v[78:81]
	v_mfma_f32_16x16x32_bf16 v[74:77], v[134:137], v[228:231], v[74:77]
	v_mfma_f32_16x16x32_bf16 v[130:133], v[146:149], v[162:165], v[130:133]
	v_mfma_f32_16x16x32_bf16 v[122:125], v[154:157], v[162:165], v[122:125]
	v_mfma_f32_16x16x32_bf16 v[102:105], v[146:149], v[170:173], v[102:105]
	v_mfma_f32_16x16x32_bf16 v[98:101], v[154:157], v[170:173], v[98:101]
	v_mfma_f32_16x16x32_bf16 v[86:89], v[146:149], v[178:181], v[86:89]
	v_mfma_f32_16x16x32_bf16 v[82:85], v[154:157], v[178:181], v[82:85]
	v_mfma_f32_16x16x32_bf16 v[70:73], v[146:149], v[224:227], v[70:73]
	v_mfma_f32_16x16x32_bf16 v[66:69], v[154:157], v[224:227], v[66:69]
	v_mfma_f32_16x16x32_bf16 v[130:133], v[150:153], v[166:169], v[130:133]
	v_mfma_f32_16x16x32_bf16 v[122:125], v[158:161], v[166:169], v[122:125]
	v_mfma_f32_16x16x32_bf16 v[102:105], v[150:153], v[174:177], v[102:105]
	v_mfma_f32_16x16x32_bf16 v[98:101], v[158:161], v[174:177], v[98:101]
	v_mfma_f32_16x16x32_bf16 v[86:89], v[150:153], v[182:185], v[86:89]
	v_mfma_f32_16x16x32_bf16 v[82:85], v[158:161], v[182:185], v[82:85]
	v_mfma_f32_16x16x32_bf16 v[70:73], v[150:153], v[228:231], v[70:73]
	v_mfma_f32_16x16x32_bf16 v[66:69], v[158:161], v[228:231], v[66:69]
	s_barrier
	s_setprio 0
	s_add_i32 s47, s47, s58
	v_lshl_add_u64 v[216:217], v[216:217], 0, s[16:17]
	s_mov_b32 m0, s47
	ds_read_b128 v[162:165], v222 offset:49152
	ds_read_b128 v[166:169], v222 offset:50176
	ds_read_b128 v[170:173], v222 offset:51200
	ds_read_b128 v[174:177], v222 offset:52224
	ds_read_b128 v[178:181], v222 offset:53248
	ds_read_b128 v[182:185], v222 offset:54272
	ds_read_b128 v[224:227], v222 offset:55296
	ds_read_b128 v[228:231], v222 offset:56320
	global_load_lds_dwordx4 v[216:217], off
	s_add_i32 m0, s47, 0x2000
	s_add_u32 s54, s54, 0x40080
	v_lshl_add_u64 v[216:217], v[240:241], 0, s[16:17]
	s_addc_u32 s55, s55, 0
	s_add_i32 s47, s68, s58
	global_load_lds_dwordx4 v[216:217], off
	v_lshl_add_u64 v[216:217], s[54:55], 0, v[208:209]
	s_mov_b32 m0, s47
	s_nop 0
	global_load_lds_dwordx4 v[216:217], off
	v_lshl_add_u64 v[216:217], s[54:55], 0, v[204:205]
	s_add_i32 m0, s47, 0x2000
	s_nop 0
	global_load_lds_dwordx4 v[216:217], off
	v_lshl_add_u64 v[216:217], v[242:243], 0, s[16:17]
	s_mov_b32 m0, s65
	s_nop 0
	global_load_lds_dwordx4 v[216:217], off
	v_lshl_add_u64 v[216:217], v[244:245], 0, s[16:17]
	s_mov_b32 m0, s66
	s_nop 0
	global_load_lds_dwordx4 v[216:217], off
	s_waitcnt vmcnt(8)
	s_waitcnt lgkmcnt(0)
	s_setprio 1
	s_barrier
	v_mfma_f32_16x16x32_bf16 v[62:65], v[106:109], v[162:165], v[62:65]
	v_mfma_f32_16x16x32_bf16 v[58:61], v[126:129], v[162:165], v[58:61]
	v_mfma_f32_16x16x32_bf16 v[46:49], v[106:109], v[170:173], v[46:49]
	v_mfma_f32_16x16x32_bf16 v[42:45], v[126:129], v[170:173], v[42:45]
	v_mfma_f32_16x16x32_bf16 v[30:33], v[106:109], v[178:181], v[30:33]
	v_mfma_f32_16x16x32_bf16 v[26:29], v[126:129], v[178:181], v[26:29]
	v_mfma_f32_16x16x32_bf16 v[14:17], v[106:109], v[224:227], v[14:17]
	v_mfma_f32_16x16x32_bf16 v[10:13], v[126:129], v[224:227], v[10:13]
	s_add_i32 s45, s45, 2
	s_add_u32 s52, s52, 0x100
	s_addc_u32 s53, s53, 0
	s_add_u32 s18, s18, 0x100
	s_addc_u32 s19, s19, 0
	v_mfma_f32_16x16x32_bf16 v[62:65], v[110:113], v[166:169], v[62:65]
	v_mfma_f32_16x16x32_bf16 v[58:61], v[134:137], v[166:169], v[58:61]
	v_mfma_f32_16x16x32_bf16 v[46:49], v[110:113], v[174:177], v[46:49]
	v_mfma_f32_16x16x32_bf16 v[42:45], v[134:137], v[174:177], v[42:45]
	v_mfma_f32_16x16x32_bf16 v[30:33], v[110:113], v[182:185], v[30:33]
	v_mfma_f32_16x16x32_bf16 v[26:29], v[134:137], v[182:185], v[26:29]
	v_mfma_f32_16x16x32_bf16 v[14:17], v[110:113], v[228:231], v[14:17]
	v_mfma_f32_16x16x32_bf16 v[10:13], v[134:137], v[228:231], v[10:13]
	v_mfma_f32_16x16x32_bf16 v[54:57], v[146:149], v[162:165], v[54:57]
	v_mfma_f32_16x16x32_bf16 v[50:53], v[154:157], v[162:165], v[50:53]
	v_mfma_f32_16x16x32_bf16 v[38:41], v[146:149], v[170:173], v[38:41]
	v_mfma_f32_16x16x32_bf16 v[34:37], v[154:157], v[170:173], v[34:37]
	v_mfma_f32_16x16x32_bf16 v[22:25], v[146:149], v[178:181], v[22:25]
	v_mfma_f32_16x16x32_bf16 v[18:21], v[154:157], v[178:181], v[18:21]
	v_mfma_f32_16x16x32_bf16 v[6:9], v[146:149], v[224:227], v[6:9]
	v_mfma_f32_16x16x32_bf16 v[2:5], v[154:157], v[224:227], v[2:5]
	v_mfma_f32_16x16x32_bf16 v[54:57], v[150:153], v[166:169], v[54:57]
	v_mfma_f32_16x16x32_bf16 v[50:53], v[158:161], v[166:169], v[50:53]
	v_mfma_f32_16x16x32_bf16 v[38:41], v[150:153], v[174:177], v[38:41]
	v_mfma_f32_16x16x32_bf16 v[34:37], v[158:161], v[174:177], v[34:37]
	v_mfma_f32_16x16x32_bf16 v[22:25], v[150:153], v[182:185], v[22:25]
	v_mfma_f32_16x16x32_bf16 v[18:21], v[158:161], v[182:185], v[18:21]
	v_mfma_f32_16x16x32_bf16 v[6:9], v[150:153], v[228:231], v[6:9]
	v_mfma_f32_16x16x32_bf16 v[2:5], v[158:161], v[228:231], v[2:5]
	s_barrier
	s_setprio 0
	s_cmp_gt_u32 s45, 13
	s_cbranch_scc0 .LBB0_900
	s_and_b64 vcc, exec, s[40:41]
	s_cbranch_vccz .LBB0_903
	s_barrier

.LBB0_997:
	s_add_u32 s52, s50, 0xfffc0080
	s_addc_u32 s53, s51, -1
	s_add_i32 s67, 0, 0x10000
	s_cmp_eq_u32 s66, 12
	s_cselect_b32 s55, s45, s53
	s_cselect_b32 s54, s62, s52
	v_add_u32_e32 v0, s67, v144
	s_cselect_b32 s53, s43, s65
	s_cselect_b32 s52, s63, s64
	s_add_i32 s70, 0, 0x14000
	ds_read_b128 v[146:149], v0
	ds_read_b128 v[150:153], v0 offset:1024
	ds_read_b128 v[154:157], v0 offset:2048
	ds_read_b128 v[158:161], v0 offset:3072
	v_add_u32_e32 v0, s70, v144
	ds_read_b128 v[162:165], v0
	ds_read_b128 v[166:169], v0 offset:1024
	ds_read_b128 v[170:173], v0 offset:2048
	ds_read_b128 v[174:177], v0 offset:3072
	s_add_i32 m0, s5, 0xc000
	ds_read_b128 v[178:181], v145
	ds_read_b128 v[182:185], v145 offset:1024
	ds_read_b128 v[204:207], v145 offset:2048
	ds_read_b128 v[208:211], v145 offset:3072
	ds_read_b128 v[212:215], v145 offset:4096
	ds_read_b128 v[220:223], v145 offset:5120
	ds_read_b128 v[224:227], v145 offset:6144
	ds_read_b128 v[228:231], v145 offset:7168
	global_load_lds_dwordx4 v138, s[50:51]
	s_add_i32 m0, s5, 0xe000
	s_nop 0
	global_load_lds_dwordx4 v140, s[50:51]
	s_waitcnt vmcnt(8)
	s_waitcnt lgkmcnt(0)
	s_setprio 1
	s_barrier
	v_mfma_f32_16x16x32_bf16 v[118:121], v[146:149], v[178:181], v[118:121]
	v_mfma_f32_16x16x32_bf16 v[114:117], v[154:157], v[178:181], v[114:117]
	v_mfma_f32_16x16x32_bf16 v[110:113], v[146:149], v[204:207], v[110:113]
	v_mfma_f32_16x16x32_bf16 v[102:105], v[154:157], v[204:207], v[102:105]
	v_mfma_f32_16x16x32_bf16 v[94:97], v[146:149], v[212:215], v[94:97]
	v_mfma_f32_16x16x32_bf16 v[86:89], v[154:157], v[212:215], v[86:89]
	v_mfma_f32_16x16x32_bf16 v[78:81], v[146:149], v[224:227], v[78:81]
	v_mfma_f32_16x16x32_bf16 v[70:73], v[154:157], v[224:227], v[70:73]
	v_mfma_f32_16x16x32_bf16 v[118:121], v[150:153], v[182:185], v[118:121]
	v_mfma_f32_16x16x32_bf16 v[114:117], v[158:161], v[182:185], v[114:117]
	v_mfma_f32_16x16x32_bf16 v[110:113], v[150:153], v[208:211], v[110:113]
	v_mfma_f32_16x16x32_bf16 v[102:105], v[158:161], v[208:211], v[102:105]
	v_mfma_f32_16x16x32_bf16 v[94:97], v[150:153], v[220:223], v[94:97]
	v_mfma_f32_16x16x32_bf16 v[86:89], v[158:161], v[220:223], v[86:89]
	v_mfma_f32_16x16x32_bf16 v[78:81], v[150:153], v[228:231], v[78:81]
	v_mfma_f32_16x16x32_bf16 v[70:73], v[158:161], v[228:231], v[70:73]
	v_mfma_f32_16x16x32_bf16 v[126:129], v[162:165], v[178:181], v[126:129]
	v_mfma_f32_16x16x32_bf16 v[122:125], v[170:173], v[178:181], v[122:125]
	v_mfma_f32_16x16x32_bf16 v[106:109], v[162:165], v[204:207], v[106:109]
	v_mfma_f32_16x16x32_bf16 v[98:101], v[170:173], v[204:207], v[98:101]
	v_mfma_f32_16x16x32_bf16 v[90:93], v[162:165], v[212:215], v[90:93]
	v_mfma_f32_16x16x32_bf16 v[82:85], v[170:173], v[212:215], v[82:85]
	v_mfma_f32_16x16x32_bf16 v[74:77], v[162:165], v[224:227], v[74:77]
	v_mfma_f32_16x16x32_bf16 v[66:69], v[170:173], v[224:227], v[66:69]
	v_mfma_f32_16x16x32_bf16 v[126:129], v[166:169], v[182:185], v[126:129]
	v_mfma_f32_16x16x32_bf16 v[122:125], v[174:177], v[182:185], v[122:125]
	v_mfma_f32_16x16x32_bf16 v[106:109], v[166:169], v[208:211], v[106:109]
	v_mfma_f32_16x16x32_bf16 v[98:101], v[174:177], v[208:211], v[98:101]
	v_mfma_f32_16x16x32_bf16 v[90:93], v[166:169], v[220:223], v[90:93]
	v_mfma_f32_16x16x32_bf16 v[82:85], v[174:177], v[220:223], v[82:85]
	v_mfma_f32_16x16x32_bf16 v[74:77], v[166:169], v[228:231], v[74:77]
	v_mfma_f32_16x16x32_bf16 v[66:69], v[174:177], v[228:231], v[66:69]
	s_barrier
	s_setprio 0
	s_add_i32 s67, s67, s4
	s_mov_b32 m0, s67
	ds_read_b128 v[178:181], v145 offset:16384
	ds_read_b128 v[182:185], v145 offset:17408
	ds_read_b128 v[204:207], v145 offset:18432
	ds_read_b128 v[208:211], v145 offset:19456
	ds_read_b128 v[212:215], v145 offset:20480
	ds_read_b128 v[220:223], v145 offset:21504
	ds_read_b128 v[224:227], v145 offset:22528
	ds_read_b128 v[228:231], v145 offset:23552
	global_load_lds_dwordx4 v134, s[52:53]
	s_add_i32 m0, s67, 0x2000
	s_add_u32 s68, s52, 0x40000
	s_addc_u32 s69, s53, 0
	s_add_i32 s67, s70, s4
	global_load_lds_dwordx4 v130, s[52:53]
	s_mov_b32 m0, s67
	s_nop 0
	global_load_lds_dwordx4 v134, s[68:69]
	s_add_i32 m0, s67, 0x2000
	s_nop 0
	global_load_lds_dwordx4 v130, s[68:69]
	s_mov_b32 m0, s5
	s_nop 0
	global_load_lds_dwordx4 v136, s[54:55]
	s_mov_b32 m0, s6
	s_nop 0
	global_load_lds_dwordx4 v132, s[54:55]
	s_waitcnt vmcnt(8)
	s_waitcnt lgkmcnt(0)
	s_setprio 1
	s_barrier
	v_mfma_f32_16x16x32_bf16 v[62:65], v[146:149], v[178:181], v[62:65]
	v_mfma_f32_16x16x32_bf16 v[54:57], v[154:157], v[178:181], v[54:57]
	v_mfma_f32_16x16x32_bf16 v[46:49], v[146:149], v[204:207], v[46:49]
	v_mfma_f32_16x16x32_bf16 v[38:41], v[154:157], v[204:207], v[38:41]
	v_mfma_f32_16x16x32_bf16 v[30:33], v[146:149], v[212:215], v[30:33]
	v_mfma_f32_16x16x32_bf16 v[22:25], v[154:157], v[212:215], v[22:25]
	v_mfma_f32_16x16x32_bf16 v[14:17], v[146:149], v[224:227], v[14:17]
	v_mfma_f32_16x16x32_bf16 v[6:9], v[154:157], v[224:227], v[6:9]
	v_mfma_f32_16x16x32_bf16 v[62:65], v[150:153], v[182:185], v[62:65]
	v_mfma_f32_16x16x32_bf16 v[54:57], v[158:161], v[182:185], v[54:57]
	v_mfma_f32_16x16x32_bf16 v[46:49], v[150:153], v[208:211], v[46:49]
	v_mfma_f32_16x16x32_bf16 v[38:41], v[158:161], v[208:211], v[38:41]
	v_mfma_f32_16x16x32_bf16 v[30:33], v[150:153], v[220:223], v[30:33]
	v_mfma_f32_16x16x32_bf16 v[22:25], v[158:161], v[220:223], v[22:25]
	v_mfma_f32_16x16x32_bf16 v[14:17], v[150:153], v[228:231], v[14:17]
	v_mfma_f32_16x16x32_bf16 v[6:9], v[158:161], v[228:231], v[6:9]
	v_mfma_f32_16x16x32_bf16 v[58:61], v[162:165], v[178:181], v[58:61]
	v_mfma_f32_16x16x32_bf16 v[50:53], v[170:173], v[178:181], v[50:53]
	v_mfma_f32_16x16x32_bf16 v[42:45], v[162:165], v[204:207], v[42:45]
	v_mfma_f32_16x16x32_bf16 v[34:37], v[170:173], v[204:207], v[34:37]
	v_mfma_f32_16x16x32_bf16 v[26:29], v[162:165], v[212:215], v[26:29]
	v_mfma_f32_16x16x32_bf16 v[18:21], v[170:173], v[212:215], v[18:21]
	v_mfma_f32_16x16x32_bf16 v[10:13], v[162:165], v[224:227], v[10:13]
	v_mfma_f32_16x16x32_bf16 v[2:5], v[170:173], v[224:227], v[2:5]
	v_mfma_f32_16x16x32_bf16 v[58:61], v[166:169], v[182:185], v[58:61]
	v_mfma_f32_16x16x32_bf16 v[50:53], v[174:177], v[182:185], v[50:53]
	v_mfma_f32_16x16x32_bf16 v[42:45], v[166:169], v[208:211], v[42:45]
	v_mfma_f32_16x16x32_bf16 v[34:37], v[174:177], v[208:211], v[34:37]
	v_mfma_f32_16x16x32_bf16 v[26:29], v[166:169], v[220:223], v[26:29]
	v_mfma_f32_16x16x32_bf16 v[18:21], v[174:177], v[220:223], v[18:21]
	v_mfma_f32_16x16x32_bf16 v[10:13], v[166:169], v[228:231], v[10:13]
	v_mfma_f32_16x16x32_bf16 v[2:5], v[174:177], v[228:231], v[2:5]
	s_barrier
	s_setprio 0
	s_add_i32 s67, 0, 0x18000
	v_add_u32_e32 v0, s67, v144
	s_add_i32 s68, 0, 0x1c000
	ds_read_b128 v[146:149], v0
	ds_read_b128 v[150:153], v0 offset:1024
	ds_read_b128 v[154:157], v0 offset:2048
	ds_read_b128 v[158:161], v0 offset:3072
	v_add_u32_e32 v0, s68, v144
	ds_read_b128 v[162:165], v0
	ds_read_b128 v[166:169], v0 offset:1024
	ds_read_b128 v[170:173], v0 offset:2048
	ds_read_b128 v[174:177], v0 offset:3072
	s_add_u32 s54, s54, 0x40000
	s_addc_u32 s55, s55, 0
	s_mov_b32 m0, s7
	ds_read_b128 v[178:181], v145 offset:32768
	ds_read_b128 v[182:185], v145 offset:33792
	ds_read_b128 v[204:207], v145 offset:34816
	ds_read_b128 v[208:211], v145 offset:35840
	ds_read_b128 v[212:215], v145 offset:36864
	ds_read_b128 v[220:223], v145 offset:37888
	ds_read_b128 v[224:227], v145 offset:38912
	ds_read_b128 v[228:231], v145 offset:39936
	global_load_lds_dwordx4 v136, s[54:55]
	s_mov_b32 m0, s56
	s_nop 0
	global_load_lds_dwordx4 v132, s[54:55]
	s_waitcnt vmcnt(8)
	s_waitcnt lgkmcnt(0)
	s_setprio 1
	s_barrier
	v_mfma_f32_16x16x32_bf16 v[118:121], v[146:149], v[178:181], v[118:121]
	v_mfma_f32_16x16x32_bf16 v[114:117], v[154:157], v[178:181], v[114:117]
	v_mfma_f32_16x16x32_bf16 v[110:113], v[146:149], v[204:207], v[110:113]
	v_mfma_f32_16x16x32_bf16 v[102:105], v[154:157], v[204:207], v[102:105]
	v_mfma_f32_16x16x32_bf16 v[94:97], v[146:149], v[212:215], v[94:97]
	v_mfma_f32_16x16x32_bf16 v[86:89], v[154:157], v[212:215], v[86:89]
	v_mfma_f32_16x16x32_bf16 v[78:81], v[146:149], v[224:227], v[78:81]
	v_mfma_f32_16x16x32_bf16 v[70:73], v[154:157], v[224:227], v[70:73]
	v_mfma_f32_16x16x32_bf16 v[118:121], v[150:153], v[182:185], v[118:121]
	v_mfma_f32_16x16x32_bf16 v[114:117], v[158:161], v[182:185], v[114:117]
	v_mfma_f32_16x16x32_bf16 v[110:113], v[150:153], v[208:211], v[110:113]
	v_mfma_f32_16x16x32_bf16 v[102:105], v[158:161], v[208:211], v[102:105]
	v_mfma_f32_16x16x32_bf16 v[94:97], v[150:153], v[220:223], v[94:97]
	v_mfma_f32_16x16x32_bf16 v[86:89], v[158:161], v[220:223], v[86:89]
	v_mfma_f32_16x16x32_bf16 v[78:81], v[150:153], v[228:231], v[78:81]
	v_mfma_f32_16x16x32_bf16 v[70:73], v[158:161], v[228:231], v[70:73]
	v_mfma_f32_16x16x32_bf16 v[126:129], v[162:165], v[178:181], v[126:129]
	v_mfma_f32_16x16x32_bf16 v[122:125], v[170:173], v[178:181], v[122:125]
	v_mfma_f32_16x16x32_bf16 v[106:109], v[162:165], v[204:207], v[106:109]
	v_mfma_f32_16x16x32_bf16 v[98:101], v[170:173], v[204:207], v[98:101]
	v_mfma_f32_16x16x32_bf16 v[90:93], v[162:165], v[212:215], v[90:93]
	v_mfma_f32_16x16x32_bf16 v[82:85], v[170:173], v[212:215], v[82:85]
	v_mfma_f32_16x16x32_bf16 v[74:77], v[162:165], v[224:227], v[74:77]
	v_mfma_f32_16x16x32_bf16 v[66:69], v[170:173], v[224:227], v[66:69]
	v_mfma_f32_16x16x32_bf16 v[126:129], v[166:169], v[182:185], v[126:129]
	v_mfma_f32_16x16x32_bf16 v[122:125], v[174:177], v[182:185], v[122:125]
	v_mfma_f32_16x16x32_bf16 v[106:109], v[166:169], v[208:211], v[106:109]
	v_mfma_f32_16x16x32_bf16 v[98:101], v[174:177], v[208:211], v[98:101]
	v_mfma_f32_16x16x32_bf16 v[90:93], v[166:169], v[220:223], v[90:93]
	v_mfma_f32_16x16x32_bf16 v[82:85], v[174:177], v[220:223], v[82:85]
	v_mfma_f32_16x16x32_bf16 v[74:77], v[166:169], v[228:231], v[74:77]
	v_mfma_f32_16x16x32_bf16 v[66:69], v[174:177], v[228:231], v[66:69]
	s_barrier
	s_setprio 0
	s_add_i32 s69, s67, s4
	s_add_u32 s52, s52, 0x80
	s_addc_u32 s53, s53, 0
	s_mov_b32 m0, s69
	ds_read_b128 v[178:181], v145 offset:49152
	ds_read_b128 v[182:185], v145 offset:50176
	ds_read_b128 v[204:207], v145 offset:51200
	ds_read_b128 v[208:211], v145 offset:52224
	ds_read_b128 v[212:215], v145 offset:53248
	ds_read_b128 v[220:223], v145 offset:54272
	ds_read_b128 v[224:227], v145 offset:55296
	ds_read_b128 v[228:231], v145 offset:56320
	global_load_lds_dwordx4 v134, s[52:53]
	s_add_i32 m0, s69, 0x2000
	s_add_i32 s69, s68, s4
	global_load_lds_dwordx4 v130, s[52:53]
	s_add_u32 s52, s52, 0x40000
	s_addc_u32 s53, s53, 0
	s_mov_b32 m0, s69
	s_sub_u32 s54, s54, 0x3ff80
	global_load_lds_dwordx4 v134, s[52:53]
	s_subb_u32 s55, s55, 0
	s_add_i32 m0, s69, 0x2000
	s_nop 0
	global_load_lds_dwordx4 v130, s[52:53]
	s_mov_b32 m0, s59
	s_nop 0
	global_load_lds_dwordx4 v136, s[54:55]
	s_mov_b32 m0, s60
	s_nop 0
	global_load_lds_dwordx4 v132, s[54:55]
	s_waitcnt vmcnt(8)
	s_waitcnt lgkmcnt(0)
	s_setprio 1
	s_barrier
	v_mfma_f32_16x16x32_bf16 v[62:65], v[146:149], v[178:181], v[62:65]
	v_mfma_f32_16x16x32_bf16 v[54:57], v[154:157], v[178:181], v[54:57]
	v_mfma_f32_16x16x32_bf16 v[46:49], v[146:149], v[204:207], v[46:49]
	v_mfma_f32_16x16x32_bf16 v[38:41], v[154:157], v[204:207], v[38:41]
	v_mfma_f32_16x16x32_bf16 v[30:33], v[146:149], v[212:215], v[30:33]
	v_mfma_f32_16x16x32_bf16 v[22:25], v[154:157], v[212:215], v[22:25]
	v_mfma_f32_16x16x32_bf16 v[14:17], v[146:149], v[224:227], v[14:17]
	v_mfma_f32_16x16x32_bf16 v[6:9], v[154:157], v[224:227], v[6:9]
	s_add_i32 s66, s66, 2
	s_add_u32 s50, s50, 0x100
	s_addc_u32 s51, s51, 0
	s_add_u32 s64, s64, 0x100
	s_addc_u32 s65, s65, 0
	v_mfma_f32_16x16x32_bf16 v[62:65], v[150:153], v[182:185], v[62:65]
	v_mfma_f32_16x16x32_bf16 v[54:57], v[158:161], v[182:185], v[54:57]
	v_mfma_f32_16x16x32_bf16 v[46:49], v[150:153], v[208:211], v[46:49]
	v_mfma_f32_16x16x32_bf16 v[38:41], v[158:161], v[208:211], v[38:41]
	v_mfma_f32_16x16x32_bf16 v[30:33], v[150:153], v[220:223], v[30:33]
	v_mfma_f32_16x16x32_bf16 v[22:25], v[158:161], v[220:223], v[22:25]
	v_mfma_f32_16x16x32_bf16 v[14:17], v[150:153], v[228:231], v[14:17]
	v_mfma_f32_16x16x32_bf16 v[6:9], v[158:161], v[228:231], v[6:9]
	v_mfma_f32_16x16x32_bf16 v[58:61], v[162:165], v[178:181], v[58:61]
	v_mfma_f32_16x16x32_bf16 v[50:53], v[170:173], v[178:181], v[50:53]
	v_mfma_f32_16x16x32_bf16 v[42:45], v[162:165], v[204:207], v[42:45]
	v_mfma_f32_16x16x32_bf16 v[34:37], v[170:173], v[204:207], v[34:37]
	v_mfma_f32_16x16x32_bf16 v[26:29], v[162:165], v[212:215], v[26:29]
	v_mfma_f32_16x16x32_bf16 v[18:21], v[170:173], v[212:215], v[18:21]
	v_mfma_f32_16x16x32_bf16 v[10:13], v[162:165], v[224:227], v[10:13]
	v_mfma_f32_16x16x32_bf16 v[2:5], v[170:173], v[224:227], v[2:5]
	v_mfma_f32_16x16x32_bf16 v[58:61], v[166:169], v[182:185], v[58:61]
	v_mfma_f32_16x16x32_bf16 v[50:53], v[174:177], v[182:185], v[50:53]
	v_mfma_f32_16x16x32_bf16 v[42:45], v[166:169], v[208:211], v[42:45]
	v_mfma_f32_16x16x32_bf16 v[34:37], v[174:177], v[208:211], v[34:37]
	v_mfma_f32_16x16x32_bf16 v[26:29], v[166:169], v[220:223], v[26:29]
	v_mfma_f32_16x16x32_bf16 v[18:21], v[174:177], v[220:223], v[18:21]
	v_mfma_f32_16x16x32_bf16 v[10:13], v[166:169], v[228:231], v[10:13]
	v_mfma_f32_16x16x32_bf16 v[2:5], v[174:177], v[228:231], v[2:5]
	s_barrier
	s_setprio 0
	s_cmp_gt_u32 s66, 13
	s_cbranch_scc0 .LBB0_997
	s_and_b64 vcc, exec, s[40:41]
	s_cbranch_vccz .LBB0_1000
	s_barrier

.LBB0_1088:
	s_add_u32 s0, s44, 0x100
	s_addc_u32 s1, s45, 0
	s_add_i32 s63, 0, 0x10000
	s_cmp_eq_u32 s62, 40
	s_cselect_b32 s51, s41, s1
	s_cselect_b32 s50, s40, s0
	v_add_u32_e32 v0, s63, v221
	s_cselect_b32 s49, s43, s47
	s_cselect_b32 s48, s42, s7
	s_add_i32 s64, 0, 0x14000
	ds_read_b128 v[106:109], v0
	ds_read_b128 v[110:113], v0 offset:1024
	ds_read_b128 v[126:129], v0 offset:2048
	ds_read_b128 v[134:137], v0 offset:3072
	v_add_u32_e32 v0, s64, v221
	ds_read_b128 v[146:149], v0
	ds_read_b128 v[150:153], v0 offset:1024
	ds_read_b128 v[154:157], v0 offset:2048
	ds_read_b128 v[158:161], v0 offset:3072
	v_lshl_add_u64 v[216:217], s[44:45], 0, v[212:213]
	s_add_i32 m0, s53, 0xc000
	ds_read_b128 v[162:165], v222
	ds_read_b128 v[166:169], v222 offset:1024
	ds_read_b128 v[170:173], v222 offset:2048
	ds_read_b128 v[174:177], v222 offset:3072
	ds_read_b128 v[178:181], v222 offset:4096
	ds_read_b128 v[182:185], v222 offset:5120
	ds_read_b128 v[224:227], v222 offset:6144
	ds_read_b128 v[228:231], v222 offset:7168
	global_load_lds_dwordx4 v[216:217], off
	v_lshl_add_u64 v[216:217], s[44:45], 0, v[214:215]
	s_add_i32 m0, s53, 0xe000
	s_nop 0
	global_load_lds_dwordx4 v[216:217], off
	s_waitcnt vmcnt(8)
	s_waitcnt lgkmcnt(0)
	s_setprio 1
	s_barrier
	v_mfma_f32_16x16x32_bf16 v[142:145], v[106:109], v[162:165], v[142:145]
	v_mfma_f32_16x16x32_bf16 v[138:141], v[126:129], v[162:165], v[138:141]
	v_mfma_f32_16x16x32_bf16 v[118:121], v[106:109], v[170:173], v[118:121]
	v_mfma_f32_16x16x32_bf16 v[114:117], v[126:129], v[170:173], v[114:117]
	v_mfma_f32_16x16x32_bf16 v[94:97], v[106:109], v[178:181], v[94:97]
	v_mfma_f32_16x16x32_bf16 v[90:93], v[126:129], v[178:181], v[90:93]
	v_mfma_f32_16x16x32_bf16 v[78:81], v[106:109], v[224:227], v[78:81]
	v_mfma_f32_16x16x32_bf16 v[74:77], v[126:129], v[224:227], v[74:77]
	v_mfma_f32_16x16x32_bf16 v[142:145], v[110:113], v[166:169], v[142:145]
	v_mfma_f32_16x16x32_bf16 v[138:141], v[134:137], v[166:169], v[138:141]
	v_mfma_f32_16x16x32_bf16 v[118:121], v[110:113], v[174:177], v[118:121]
	v_mfma_f32_16x16x32_bf16 v[114:117], v[134:137], v[174:177], v[114:117]
	v_mfma_f32_16x16x32_bf16 v[94:97], v[110:113], v[182:185], v[94:97]
	v_mfma_f32_16x16x32_bf16 v[90:93], v[134:137], v[182:185], v[90:93]
	v_mfma_f32_16x16x32_bf16 v[78:81], v[110:113], v[228:231], v[78:81]
	v_mfma_f32_16x16x32_bf16 v[74:77], v[134:137], v[228:231], v[74:77]
	v_mfma_f32_16x16x32_bf16 v[130:133], v[146:149], v[162:165], v[130:133]
	v_mfma_f32_16x16x32_bf16 v[122:125], v[154:157], v[162:165], v[122:125]
	v_mfma_f32_16x16x32_bf16 v[102:105], v[146:149], v[170:173], v[102:105]
	v_mfma_f32_16x16x32_bf16 v[98:101], v[154:157], v[170:173], v[98:101]
	v_mfma_f32_16x16x32_bf16 v[86:89], v[146:149], v[178:181], v[86:89]
	v_mfma_f32_16x16x32_bf16 v[82:85], v[154:157], v[178:181], v[82:85]
	v_mfma_f32_16x16x32_bf16 v[70:73], v[146:149], v[224:227], v[70:73]
	v_mfma_f32_16x16x32_bf16 v[66:69], v[154:157], v[224:227], v[66:69]
	v_mfma_f32_16x16x32_bf16 v[130:133], v[150:153], v[166:169], v[130:133]
	v_mfma_f32_16x16x32_bf16 v[122:125], v[158:161], v[166:169], v[122:125]
	v_mfma_f32_16x16x32_bf16 v[102:105], v[150:153], v[174:177], v[102:105]
	v_mfma_f32_16x16x32_bf16 v[98:101], v[158:161], v[174:177], v[98:101]
	v_mfma_f32_16x16x32_bf16 v[86:89], v[150:153], v[182:185], v[86:89]
	v_mfma_f32_16x16x32_bf16 v[82:85], v[158:161], v[182:185], v[82:85]
	v_mfma_f32_16x16x32_bf16 v[70:73], v[150:153], v[228:231], v[70:73]
	v_mfma_f32_16x16x32_bf16 v[66:69], v[158:161], v[228:231], v[66:69]
	s_barrier
	s_setprio 0
	s_add_i32 s44, s63, s52
	v_lshl_add_u64 v[216:217], s[48:49], 0, v[208:209]
	s_mov_b32 m0, s44
	ds_read_b128 v[162:165], v222 offset:16384
	ds_read_b128 v[166:169], v222 offset:17408
	ds_read_b128 v[170:173], v222 offset:18432
	ds_read_b128 v[174:177], v222 offset:19456
	ds_read_b128 v[178:181], v222 offset:20480
	ds_read_b128 v[182:185], v222 offset:21504
	ds_read_b128 v[224:227], v222 offset:22528
	ds_read_b128 v[228:231], v222 offset:23552
	global_load_lds_dwordx4 v[216:217], off
	s_add_i32 m0, s44, 0x2000
	s_add_u32 s44, s48, 0xb0000
	v_lshl_add_u64 v[240:241], s[48:49], 0, v[204:205]
	s_addc_u32 s45, s49, 0
	s_add_i32 s63, s64, s52
	global_load_lds_dwordx4 v[240:241], off
	v_lshl_add_u64 v[242:243], s[44:45], 0, v[208:209]
	s_mov_b32 m0, s63
	v_lshl_add_u64 v[244:245], s[50:51], 0, v[206:207]
	global_load_lds_dwordx4 v[242:243], off
	v_lshl_add_u64 v[242:243], s[44:45], 0, v[204:205]
	s_add_i32 m0, s63, 0x2000
	s_nop 0
	global_load_lds_dwordx4 v[242:243], off
	v_lshl_add_u64 v[242:243], s[50:51], 0, v[210:211]
	s_mov_b32 m0, s53
	s_nop 0
	global_load_lds_dwordx4 v[242:243], off
	s_mov_b32 m0, s54
	s_nop 0
	global_load_lds_dwordx4 v[244:245], off
	s_waitcnt vmcnt(8)
	s_waitcnt lgkmcnt(0)
	s_setprio 1
	s_barrier
	v_mfma_f32_16x16x32_bf16 v[62:65], v[106:109], v[162:165], v[62:65]
	v_mfma_f32_16x16x32_bf16 v[58:61], v[126:129], v[162:165], v[58:61]
	v_mfma_f32_16x16x32_bf16 v[46:49], v[106:109], v[170:173], v[46:49]
	v_mfma_f32_16x16x32_bf16 v[42:45], v[126:129], v[170:173], v[42:45]
	v_mfma_f32_16x16x32_bf16 v[30:33], v[106:109], v[178:181], v[30:33]
	v_mfma_f32_16x16x32_bf16 v[26:29], v[126:129], v[178:181], v[26:29]
	v_mfma_f32_16x16x32_bf16 v[14:17], v[106:109], v[224:227], v[14:17]
	v_mfma_f32_16x16x32_bf16 v[10:13], v[126:129], v[224:227], v[10:13]
	v_mfma_f32_16x16x32_bf16 v[62:65], v[110:113], v[166:169], v[62:65]
	v_mfma_f32_16x16x32_bf16 v[58:61], v[134:137], v[166:169], v[58:61]
	v_mfma_f32_16x16x32_bf16 v[46:49], v[110:113], v[174:177], v[46:49]
	v_mfma_f32_16x16x32_bf16 v[42:45], v[134:137], v[174:177], v[42:45]
	v_mfma_f32_16x16x32_bf16 v[30:33], v[110:113], v[182:185], v[30:33]
	v_mfma_f32_16x16x32_bf16 v[26:29], v[134:137], v[182:185], v[26:29]
	v_mfma_f32_16x16x32_bf16 v[14:17], v[110:113], v[228:231], v[14:17]
	v_mfma_f32_16x16x32_bf16 v[10:13], v[134:137], v[228:231], v[10:13]
	v_mfma_f32_16x16x32_bf16 v[54:57], v[146:149], v[162:165], v[54:57]
	v_mfma_f32_16x16x32_bf16 v[50:53], v[154:157], v[162:165], v[50:53]
	v_mfma_f32_16x16x32_bf16 v[38:41], v[146:149], v[170:173], v[38:41]
	v_mfma_f32_16x16x32_bf16 v[34:37], v[154:157], v[170:173], v[34:37]
	v_mfma_f32_16x16x32_bf16 v[22:25], v[146:149], v[178:181], v[22:25]
	v_mfma_f32_16x16x32_bf16 v[18:21], v[154:157], v[178:181], v[18:21]
	v_mfma_f32_16x16x32_bf16 v[6:9], v[146:149], v[224:227], v[6:9]
	v_mfma_f32_16x16x32_bf16 v[2:5], v[154:157], v[224:227], v[2:5]
	v_mfma_f32_16x16x32_bf16 v[54:57], v[150:153], v[166:169], v[54:57]
	v_mfma_f32_16x16x32_bf16 v[50:53], v[158:161], v[166:169], v[50:53]
	v_mfma_f32_16x16x32_bf16 v[38:41], v[150:153], v[174:177], v[38:41]
	v_mfma_f32_16x16x32_bf16 v[34:37], v[158:161], v[174:177], v[34:37]
	v_mfma_f32_16x16x32_bf16 v[22:25], v[150:153], v[182:185], v[22:25]
	v_mfma_f32_16x16x32_bf16 v[18:21], v[158:161], v[182:185], v[18:21]
	v_mfma_f32_16x16x32_bf16 v[6:9], v[150:153], v[228:231], v[6:9]
	v_mfma_f32_16x16x32_bf16 v[2:5], v[158:161], v[228:231], v[2:5]
	s_barrier
	s_setprio 0
	s_add_i32 s63, 0, 0x18000
	v_add_u32_e32 v0, s63, v221
	s_add_i32 s64, 0, 0x1c000
	ds_read_b128 v[106:109], v0
	ds_read_b128 v[110:113], v0 offset:1024
	ds_read_b128 v[126:129], v0 offset:2048
	ds_read_b128 v[134:137], v0 offset:3072
	v_add_u32_e32 v0, s64, v221
	ds_read_b128 v[146:149], v0
	ds_read_b128 v[150:153], v0 offset:1024
	ds_read_b128 v[154:157], v0 offset:2048
	ds_read_b128 v[158:161], v0 offset:3072
	s_add_u32 s44, s50, 0xb0000
	s_addc_u32 s45, s51, 0
	s_mov_b32 m0, s55
	v_lshl_add_u64 v[246:247], s[44:45], 0, v[210:211]
	ds_read_b128 v[162:165], v222 offset:32768
	ds_read_b128 v[166:169], v222 offset:33792
	ds_read_b128 v[170:173], v222 offset:34816
	ds_read_b128 v[174:177], v222 offset:35840
	ds_read_b128 v[178:181], v222 offset:36864
	ds_read_b128 v[182:185], v222 offset:37888
	ds_read_b128 v[224:227], v222 offset:38912
	ds_read_b128 v[228:231], v222 offset:39936
	global_load_lds_dwordx4 v[246:247], off
	v_lshl_add_u64 v[246:247], s[44:45], 0, v[206:207]
	s_mov_b32 m0, s56
	s_nop 0
	global_load_lds_dwordx4 v[246:247], off
	s_waitcnt vmcnt(8)
	s_waitcnt lgkmcnt(0)
	s_setprio 1
	s_barrier
	v_mfma_f32_16x16x32_bf16 v[142:145], v[106:109], v[162:165], v[142:145]
	v_mfma_f32_16x16x32_bf16 v[138:141], v[126:129], v[162:165], v[138:141]
	v_mfma_f32_16x16x32_bf16 v[118:121], v[106:109], v[170:173], v[118:121]
	v_mfma_f32_16x16x32_bf16 v[114:117], v[126:129], v[170:173], v[114:117]
	v_mfma_f32_16x16x32_bf16 v[94:97], v[106:109], v[178:181], v[94:97]
	v_mfma_f32_16x16x32_bf16 v[90:93], v[126:129], v[178:181], v[90:93]
	v_mfma_f32_16x16x32_bf16 v[78:81], v[106:109], v[224:227], v[78:81]
	v_mfma_f32_16x16x32_bf16 v[74:77], v[126:129], v[224:227], v[74:77]
	v_mfma_f32_16x16x32_bf16 v[142:145], v[110:113], v[166:169], v[142:145]
	v_mfma_f32_16x16x32_bf16 v[138:141], v[134:137], v[166:169], v[138:141]
	v_mfma_f32_16x16x32_bf16 v[118:121], v[110:113], v[174:177], v[118:121]
	v_mfma_f32_16x16x32_bf16 v[114:117], v[134:137], v[174:177], v[114:117]
	v_mfma_f32_16x16x32_bf16 v[94:97], v[110:113], v[182:185], v[94:97]
	v_mfma_f32_16x16x32_bf16 v[90:93], v[134:137], v[182:185], v[90:93]
	v_mfma_f32_16x16x32_bf16 v[78:81], v[110:113], v[228:231], v[78:81]
	v_mfma_f32_16x16x32_bf16 v[74:77], v[134:137], v[228:231], v[74:77]
	v_mfma_f32_16x16x32_bf16 v[130:133], v[146:149], v[162:165], v[130:133]
	v_mfma_f32_16x16x32_bf16 v[122:125], v[154:157], v[162:165], v[122:125]
	v_mfma_f32_16x16x32_bf16 v[102:105], v[146:149], v[170:173], v[102:105]
	v_mfma_f32_16x16x32_bf16 v[98:101], v[154:157], v[170:173], v[98:101]
	v_mfma_f32_16x16x32_bf16 v[86:89], v[146:149], v[178:181], v[86:89]
	v_mfma_f32_16x16x32_bf16 v[82:85], v[154:157], v[178:181], v[82:85]
	v_mfma_f32_16x16x32_bf16 v[70:73], v[146:149], v[224:227], v[70:73]
	v_mfma_f32_16x16x32_bf16 v[66:69], v[154:157], v[224:227], v[66:69]
	v_mfma_f32_16x16x32_bf16 v[130:133], v[150:153], v[166:169], v[130:133]
	v_mfma_f32_16x16x32_bf16 v[122:125], v[158:161], v[166:169], v[122:125]
	v_mfma_f32_16x16x32_bf16 v[102:105], v[150:153], v[174:177], v[102:105]
	v_mfma_f32_16x16x32_bf16 v[98:101], v[158:161], v[174:177], v[98:101]
	v_mfma_f32_16x16x32_bf16 v[86:89], v[150:153], v[182:185], v[86:89]
	v_mfma_f32_16x16x32_bf16 v[82:85], v[158:161], v[182:185], v[82:85]
	v_mfma_f32_16x16x32_bf16 v[70:73], v[150:153], v[228:231], v[70:73]
	v_mfma_f32_16x16x32_bf16 v[66:69], v[158:161], v[228:231], v[66:69]
	s_barrier
	s_setprio 0
	s_add_i32 s44, s63, s52
	v_lshl_add_u64 v[216:217], v[216:217], 0, s[16:17]
	s_mov_b32 m0, s44
	ds_read_b128 v[162:165], v222 offset:49152
	ds_read_b128 v[166:169], v222 offset:50176
	ds_read_b128 v[170:173], v222 offset:51200
	ds_read_b128 v[174:177], v222 offset:52224
	ds_read_b128 v[178:181], v222 offset:53248
	ds_read_b128 v[182:185], v222 offset:54272
	ds_read_b128 v[224:227], v222 offset:55296
	ds_read_b128 v[228:231], v222 offset:56320
	global_load_lds_dwordx4 v[216:217], off
	s_add_i32 m0, s44, 0x2000
	s_add_u32 s44, s48, 0xb0080
	v_lshl_add_u64 v[216:217], v[240:241], 0, s[16:17]
	s_addc_u32 s45, s49, 0
	s_add_i32 s48, s64, s52
	global_load_lds_dwordx4 v[216:217], off
	v_lshl_add_u64 v[216:217], s[44:45], 0, v[208:209]
	s_mov_b32 m0, s48
	s_nop 0
	global_load_lds_dwordx4 v[216:217], off
	v_lshl_add_u64 v[216:217], s[44:45], 0, v[204:205]
	s_add_i32 m0, s48, 0x2000
	s_nop 0
	global_load_lds_dwordx4 v[216:217], off
	v_lshl_add_u64 v[216:217], v[242:243], 0, s[16:17]
	s_mov_b32 m0, s59
	s_nop 0
	global_load_lds_dwordx4 v[216:217], off
	v_lshl_add_u64 v[216:217], v[244:245], 0, s[16:17]
	s_mov_b32 m0, s60
	s_nop 0
	global_load_lds_dwordx4 v[216:217], off
	s_waitcnt vmcnt(8)
	s_waitcnt lgkmcnt(0)
	s_setprio 1
	s_barrier
	v_mfma_f32_16x16x32_bf16 v[62:65], v[106:109], v[162:165], v[62:65]
	v_mfma_f32_16x16x32_bf16 v[58:61], v[126:129], v[162:165], v[58:61]
	v_mfma_f32_16x16x32_bf16 v[46:49], v[106:109], v[170:173], v[46:49]
	v_mfma_f32_16x16x32_bf16 v[42:45], v[126:129], v[170:173], v[42:45]
	v_mfma_f32_16x16x32_bf16 v[30:33], v[106:109], v[178:181], v[30:33]
	v_mfma_f32_16x16x32_bf16 v[26:29], v[126:129], v[178:181], v[26:29]
	v_mfma_f32_16x16x32_bf16 v[14:17], v[106:109], v[224:227], v[14:17]
	v_mfma_f32_16x16x32_bf16 v[10:13], v[126:129], v[224:227], v[10:13]
	s_add_i32 s62, s62, 2
	s_add_u32 s7, s7, 0x100
	s_addc_u32 s47, s47, 0
	v_mfma_f32_16x16x32_bf16 v[62:65], v[110:113], v[166:169], v[62:65]
	v_mfma_f32_16x16x32_bf16 v[58:61], v[134:137], v[166:169], v[58:61]
	v_mfma_f32_16x16x32_bf16 v[46:49], v[110:113], v[174:177], v[46:49]
	v_mfma_f32_16x16x32_bf16 v[42:45], v[134:137], v[174:177], v[42:45]
	v_mfma_f32_16x16x32_bf16 v[30:33], v[110:113], v[182:185], v[30:33]
	v_mfma_f32_16x16x32_bf16 v[26:29], v[134:137], v[182:185], v[26:29]
	v_mfma_f32_16x16x32_bf16 v[14:17], v[110:113], v[228:231], v[14:17]
	v_mfma_f32_16x16x32_bf16 v[10:13], v[134:137], v[228:231], v[10:13]
	v_mfma_f32_16x16x32_bf16 v[54:57], v[146:149], v[162:165], v[54:57]
	v_mfma_f32_16x16x32_bf16 v[50:53], v[154:157], v[162:165], v[50:53]
	v_mfma_f32_16x16x32_bf16 v[38:41], v[146:149], v[170:173], v[38:41]
	v_mfma_f32_16x16x32_bf16 v[34:37], v[154:157], v[170:173], v[34:37]
	v_mfma_f32_16x16x32_bf16 v[22:25], v[146:149], v[178:181], v[22:25]
	v_mfma_f32_16x16x32_bf16 v[18:21], v[154:157], v[178:181], v[18:21]
	v_mfma_f32_16x16x32_bf16 v[6:9], v[146:149], v[224:227], v[6:9]
	v_mfma_f32_16x16x32_bf16 v[2:5], v[154:157], v[224:227], v[2:5]
	v_mfma_f32_16x16x32_bf16 v[54:57], v[150:153], v[166:169], v[54:57]
	v_mfma_f32_16x16x32_bf16 v[50:53], v[158:161], v[166:169], v[50:53]
	v_mfma_f32_16x16x32_bf16 v[38:41], v[150:153], v[174:177], v[38:41]
	v_mfma_f32_16x16x32_bf16 v[34:37], v[158:161], v[174:177], v[34:37]
	v_mfma_f32_16x16x32_bf16 v[22:25], v[150:153], v[182:185], v[22:25]
	v_mfma_f32_16x16x32_bf16 v[18:21], v[158:161], v[182:185], v[18:21]
	v_mfma_f32_16x16x32_bf16 v[6:9], v[150:153], v[228:231], v[6:9]
	v_mfma_f32_16x16x32_bf16 v[2:5], v[158:161], v[228:231], v[2:5]
	s_barrier
	s_setprio 0
	s_cmp_gt_u32 s62, 41
	s_mov_b64 s[44:45], s[0:1]
	s_cbranch_scc0 .LBB0_1088
	s_and_b64 vcc, exec, s[22:23]
	s_cbranch_vccz .LBB0_1091
	s_barrier

.LBB0_1186:
	s_add_u32 s42, s40, 0xfffc0080
	s_addc_u32 s43, s41, -1
	s_add_i32 s54, 0, 0x10000
	s_cmp_eq_u32 s53, 12
	s_cselect_b32 s49, s7, s43
	s_cselect_b32 s48, s23, s42
	v_add_u32_e32 v0, s54, v160
	s_cselect_b32 s43, s21, s52
	s_cselect_b32 s42, s50, s51
	s_add_i32 s65, 0, 0x14000
	ds_read_b128 v[142:145], v0
	ds_read_b128 v[146:149], v0 offset:1024
	ds_read_b128 v[150:153], v0 offset:2048
	ds_read_b128 v[154:157], v0 offset:3072
	v_add_u32_e32 v0, s65, v160
	ds_read_b128 v[162:165], v0
	ds_read_b128 v[166:169], v0 offset:1024
	ds_read_b128 v[170:173], v0 offset:2048
	ds_read_b128 v[174:177], v0 offset:3072
	v_lshl_add_u64 v[228:229], s[40:41], 0, v[138:139]
	s_add_i32 m0, s57, 0xc000
	ds_read_b128 v[178:181], v161
	ds_read_b128 v[182:185], v161 offset:1024
	ds_read_b128 v[204:207], v161 offset:2048
	ds_read_b128 v[208:211], v161 offset:3072
	ds_read_b128 v[212:215], v161 offset:4096
	ds_read_b128 v[216:219], v161 offset:5120
	ds_read_b128 v[220:223], v161 offset:6144
	ds_read_b128 v[224:227], v161 offset:7168
	global_load_lds_dwordx4 v[228:229], off
	v_lshl_add_u64 v[228:229], s[40:41], 0, v[140:141]
	s_add_i32 m0, s57, 0xe000
	s_nop 0
	global_load_lds_dwordx4 v[228:229], off
	s_waitcnt vmcnt(8)
	s_waitcnt lgkmcnt(0)
	s_setprio 1
	s_barrier
	v_mfma_f32_16x16x32_bf16 v[126:129], v[142:145], v[178:181], v[126:129]
	v_mfma_f32_16x16x32_bf16 v[122:125], v[150:153], v[178:181], v[122:125]
	v_mfma_f32_16x16x32_bf16 v[110:113], v[142:145], v[204:207], v[110:113]
	v_mfma_f32_16x16x32_bf16 v[106:109], v[150:153], v[204:207], v[106:109]
	v_mfma_f32_16x16x32_bf16 v[94:97], v[142:145], v[212:215], v[94:97]
	v_mfma_f32_16x16x32_bf16 v[90:93], v[150:153], v[212:215], v[90:93]
	v_mfma_f32_16x16x32_bf16 v[78:81], v[142:145], v[220:223], v[78:81]
	v_mfma_f32_16x16x32_bf16 v[74:77], v[150:153], v[220:223], v[74:77]
	v_mfma_f32_16x16x32_bf16 v[126:129], v[146:149], v[182:185], v[126:129]
	v_mfma_f32_16x16x32_bf16 v[122:125], v[154:157], v[182:185], v[122:125]
	v_mfma_f32_16x16x32_bf16 v[110:113], v[146:149], v[208:211], v[110:113]
	v_mfma_f32_16x16x32_bf16 v[106:109], v[154:157], v[208:211], v[106:109]
	v_mfma_f32_16x16x32_bf16 v[94:97], v[146:149], v[216:219], v[94:97]
	v_mfma_f32_16x16x32_bf16 v[90:93], v[154:157], v[216:219], v[90:93]
	v_mfma_f32_16x16x32_bf16 v[78:81], v[146:149], v[224:227], v[78:81]
	v_mfma_f32_16x16x32_bf16 v[74:77], v[154:157], v[224:227], v[74:77]
	v_mfma_f32_16x16x32_bf16 v[118:121], v[162:165], v[178:181], v[118:121]
	v_mfma_f32_16x16x32_bf16 v[114:117], v[170:173], v[178:181], v[114:117]
	v_mfma_f32_16x16x32_bf16 v[102:105], v[162:165], v[204:207], v[102:105]
	v_mfma_f32_16x16x32_bf16 v[98:101], v[170:173], v[204:207], v[98:101]
	v_mfma_f32_16x16x32_bf16 v[86:89], v[162:165], v[212:215], v[86:89]
	v_mfma_f32_16x16x32_bf16 v[82:85], v[170:173], v[212:215], v[82:85]
	v_mfma_f32_16x16x32_bf16 v[70:73], v[162:165], v[220:223], v[70:73]
	v_mfma_f32_16x16x32_bf16 v[66:69], v[170:173], v[220:223], v[66:69]
	v_mfma_f32_16x16x32_bf16 v[118:121], v[166:169], v[182:185], v[118:121]
	v_mfma_f32_16x16x32_bf16 v[114:117], v[174:177], v[182:185], v[114:117]
	v_mfma_f32_16x16x32_bf16 v[102:105], v[166:169], v[208:211], v[102:105]
	v_mfma_f32_16x16x32_bf16 v[98:101], v[174:177], v[208:211], v[98:101]
	v_mfma_f32_16x16x32_bf16 v[86:89], v[166:169], v[216:219], v[86:89]
	v_mfma_f32_16x16x32_bf16 v[82:85], v[174:177], v[216:219], v[82:85]
	v_mfma_f32_16x16x32_bf16 v[70:73], v[166:169], v[224:227], v[70:73]
	v_mfma_f32_16x16x32_bf16 v[66:69], v[174:177], v[224:227], v[66:69]
	s_barrier
	s_setprio 0
	s_add_i32 s54, s54, s56
	v_lshl_add_u64 v[228:229], s[42:43], 0, v[134:135]
	s_mov_b32 m0, s54
	ds_read_b128 v[178:181], v161 offset:16384
	ds_read_b128 v[182:185], v161 offset:17408
	ds_read_b128 v[204:207], v161 offset:18432
	ds_read_b128 v[208:211], v161 offset:19456
	ds_read_b128 v[212:215], v161 offset:20480
	ds_read_b128 v[216:219], v161 offset:21504
	ds_read_b128 v[220:223], v161 offset:22528
	ds_read_b128 v[224:227], v161 offset:23552
	global_load_lds_dwordx4 v[228:229], off
	s_add_i32 m0, s54, 0x2000
	s_add_u32 s54, s42, 0x40000
	v_lshl_add_u64 v[230:231], s[42:43], 0, v[130:131]
	s_addc_u32 s55, s43, 0
	s_add_i32 s65, s65, s56
	global_load_lds_dwordx4 v[230:231], off
	v_lshl_add_u64 v[240:241], s[54:55], 0, v[134:135]
	s_mov_b32 m0, s65
	v_lshl_add_u64 v[242:243], s[48:49], 0, v[132:133]
	global_load_lds_dwordx4 v[240:241], off
	v_lshl_add_u64 v[240:241], s[54:55], 0, v[130:131]
	s_add_i32 m0, s65, 0x2000
	s_nop 0
	global_load_lds_dwordx4 v[240:241], off
	v_lshl_add_u64 v[240:241], s[48:49], 0, v[136:137]
	s_mov_b32 m0, s57
	s_nop 0
	global_load_lds_dwordx4 v[240:241], off
	s_mov_b32 m0, s58
	s_nop 0
	global_load_lds_dwordx4 v[242:243], off
	s_waitcnt vmcnt(8)
	s_waitcnt lgkmcnt(0)
	s_setprio 1
	s_barrier
	v_mfma_f32_16x16x32_bf16 v[62:65], v[142:145], v[178:181], v[62:65]
	v_mfma_f32_16x16x32_bf16 v[58:61], v[150:153], v[178:181], v[58:61]
	v_mfma_f32_16x16x32_bf16 v[46:49], v[142:145], v[204:207], v[46:49]
	v_mfma_f32_16x16x32_bf16 v[42:45], v[150:153], v[204:207], v[42:45]
	v_mfma_f32_16x16x32_bf16 v[30:33], v[142:145], v[212:215], v[30:33]
	v_mfma_f32_16x16x32_bf16 v[26:29], v[150:153], v[212:215], v[26:29]
	v_mfma_f32_16x16x32_bf16 v[14:17], v[142:145], v[220:223], v[14:17]
	v_mfma_f32_16x16x32_bf16 v[10:13], v[150:153], v[220:223], v[10:13]
	v_mfma_f32_16x16x32_bf16 v[62:65], v[146:149], v[182:185], v[62:65]
	v_mfma_f32_16x16x32_bf16 v[58:61], v[154:157], v[182:185], v[58:61]
	v_mfma_f32_16x16x32_bf16 v[46:49], v[146:149], v[208:211], v[46:49]
	v_mfma_f32_16x16x32_bf16 v[42:45], v[154:157], v[208:211], v[42:45]
	v_mfma_f32_16x16x32_bf16 v[30:33], v[146:149], v[216:219], v[30:33]
	v_mfma_f32_16x16x32_bf16 v[26:29], v[154:157], v[216:219], v[26:29]
	v_mfma_f32_16x16x32_bf16 v[14:17], v[146:149], v[224:227], v[14:17]
	v_mfma_f32_16x16x32_bf16 v[10:13], v[154:157], v[224:227], v[10:13]
	v_mfma_f32_16x16x32_bf16 v[54:57], v[162:165], v[178:181], v[54:57]
	v_mfma_f32_16x16x32_bf16 v[50:53], v[170:173], v[178:181], v[50:53]
	v_mfma_f32_16x16x32_bf16 v[38:41], v[162:165], v[204:207], v[38:41]
	v_mfma_f32_16x16x32_bf16 v[34:37], v[170:173], v[204:207], v[34:37]
	v_mfma_f32_16x16x32_bf16 v[22:25], v[162:165], v[212:215], v[22:25]
	v_mfma_f32_16x16x32_bf16 v[18:21], v[170:173], v[212:215], v[18:21]
	v_mfma_f32_16x16x32_bf16 v[6:9], v[162:165], v[220:223], v[6:9]
	v_mfma_f32_16x16x32_bf16 v[2:5], v[170:173], v[220:223], v[2:5]
	v_mfma_f32_16x16x32_bf16 v[54:57], v[166:169], v[182:185], v[54:57]
	v_mfma_f32_16x16x32_bf16 v[50:53], v[174:177], v[182:185], v[50:53]
	v_mfma_f32_16x16x32_bf16 v[38:41], v[166:169], v[208:211], v[38:41]
	v_mfma_f32_16x16x32_bf16 v[34:37], v[174:177], v[208:211], v[34:37]
	v_mfma_f32_16x16x32_bf16 v[22:25], v[166:169], v[216:219], v[22:25]
	v_mfma_f32_16x16x32_bf16 v[18:21], v[174:177], v[216:219], v[18:21]
	v_mfma_f32_16x16x32_bf16 v[6:9], v[166:169], v[224:227], v[6:9]
	v_mfma_f32_16x16x32_bf16 v[2:5], v[174:177], v[224:227], v[2:5]
	s_barrier
	s_setprio 0
	s_add_i32 s54, 0, 0x18000
	v_add_u32_e32 v0, s54, v160
	s_add_i32 s55, 0, 0x1c000
	ds_read_b128 v[142:145], v0
	ds_read_b128 v[146:149], v0 offset:1024
	ds_read_b128 v[150:153], v0 offset:2048
	ds_read_b128 v[154:157], v0 offset:3072
	v_add_u32_e32 v0, s55, v160
	ds_read_b128 v[162:165], v0
	ds_read_b128 v[166:169], v0 offset:1024
	ds_read_b128 v[170:173], v0 offset:2048
	ds_read_b128 v[174:177], v0 offset:3072
	s_add_u32 s48, s48, 0x40000
	s_addc_u32 s49, s49, 0
	s_mov_b32 m0, s59
	v_lshl_add_u64 v[244:245], s[48:49], 0, v[136:137]
	ds_read_b128 v[178:181], v161 offset:32768
	ds_read_b128 v[182:185], v161 offset:33792
	ds_read_b128 v[204:207], v161 offset:34816
	ds_read_b128 v[208:211], v161 offset:35840
	ds_read_b128 v[212:215], v161 offset:36864
	ds_read_b128 v[216:219], v161 offset:37888
	ds_read_b128 v[220:223], v161 offset:38912
	ds_read_b128 v[224:227], v161 offset:39936
	global_load_lds_dwordx4 v[244:245], off
	v_lshl_add_u64 v[244:245], s[48:49], 0, v[132:133]
	s_mov_b32 m0, s60
	s_nop 0
	global_load_lds_dwordx4 v[244:245], off
	s_waitcnt vmcnt(8)
	s_waitcnt lgkmcnt(0)
	s_setprio 1
	s_barrier
	v_mfma_f32_16x16x32_bf16 v[126:129], v[142:145], v[178:181], v[126:129]
	v_mfma_f32_16x16x32_bf16 v[122:125], v[150:153], v[178:181], v[122:125]
	v_mfma_f32_16x16x32_bf16 v[110:113], v[142:145], v[204:207], v[110:113]
	v_mfma_f32_16x16x32_bf16 v[106:109], v[150:153], v[204:207], v[106:109]
	v_mfma_f32_16x16x32_bf16 v[94:97], v[142:145], v[212:215], v[94:97]
	v_mfma_f32_16x16x32_bf16 v[90:93], v[150:153], v[212:215], v[90:93]
	v_mfma_f32_16x16x32_bf16 v[78:81], v[142:145], v[220:223], v[78:81]
	v_mfma_f32_16x16x32_bf16 v[74:77], v[150:153], v[220:223], v[74:77]
	v_mfma_f32_16x16x32_bf16 v[126:129], v[146:149], v[182:185], v[126:129]
	v_mfma_f32_16x16x32_bf16 v[122:125], v[154:157], v[182:185], v[122:125]
	v_mfma_f32_16x16x32_bf16 v[110:113], v[146:149], v[208:211], v[110:113]
	v_mfma_f32_16x16x32_bf16 v[106:109], v[154:157], v[208:211], v[106:109]
	v_mfma_f32_16x16x32_bf16 v[94:97], v[146:149], v[216:219], v[94:97]
	v_mfma_f32_16x16x32_bf16 v[90:93], v[154:157], v[216:219], v[90:93]
	v_mfma_f32_16x16x32_bf16 v[78:81], v[146:149], v[224:227], v[78:81]
	v_mfma_f32_16x16x32_bf16 v[74:77], v[154:157], v[224:227], v[74:77]
	v_mfma_f32_16x16x32_bf16 v[118:121], v[162:165], v[178:181], v[118:121]
	v_mfma_f32_16x16x32_bf16 v[114:117], v[170:173], v[178:181], v[114:117]
	v_mfma_f32_16x16x32_bf16 v[102:105], v[162:165], v[204:207], v[102:105]
	v_mfma_f32_16x16x32_bf16 v[98:101], v[170:173], v[204:207], v[98:101]
	v_mfma_f32_16x16x32_bf16 v[86:89], v[162:165], v[212:215], v[86:89]
	v_mfma_f32_16x16x32_bf16 v[82:85], v[170:173], v[212:215], v[82:85]
	v_mfma_f32_16x16x32_bf16 v[70:73], v[162:165], v[220:223], v[70:73]
	v_mfma_f32_16x16x32_bf16 v[66:69], v[170:173], v[220:223], v[66:69]
	v_mfma_f32_16x16x32_bf16 v[118:121], v[166:169], v[182:185], v[118:121]
	v_mfma_f32_16x16x32_bf16 v[114:117], v[174:177], v[182:185], v[114:117]
	v_mfma_f32_16x16x32_bf16 v[102:105], v[166:169], v[208:211], v[102:105]
	v_mfma_f32_16x16x32_bf16 v[98:101], v[174:177], v[208:211], v[98:101]
	v_mfma_f32_16x16x32_bf16 v[86:89], v[166:169], v[216:219], v[86:89]
	v_mfma_f32_16x16x32_bf16 v[82:85], v[174:177], v[216:219], v[82:85]
	v_mfma_f32_16x16x32_bf16 v[70:73], v[166:169], v[224:227], v[70:73]
	v_mfma_f32_16x16x32_bf16 v[66:69], v[174:177], v[224:227], v[66:69]
	s_barrier
	s_setprio 0
	s_add_i32 s48, s54, s56
	v_lshl_add_u64 v[228:229], v[228:229], 0, s[16:17]
	s_mov_b32 m0, s48
	ds_read_b128 v[178:181], v161 offset:49152
	ds_read_b128 v[182:185], v161 offset:50176
	ds_read_b128 v[204:207], v161 offset:51200
	ds_read_b128 v[208:211], v161 offset:52224
	ds_read_b128 v[212:215], v161 offset:53248
	ds_read_b128 v[216:219], v161 offset:54272
	ds_read_b128 v[220:223], v161 offset:55296
	ds_read_b128 v[224:227], v161 offset:56320
	global_load_lds_dwordx4 v[228:229], off
	s_add_i32 m0, s48, 0x2000
	s_add_u32 s42, s42, 0x40080
	v_lshl_add_u64 v[228:229], v[230:231], 0, s[16:17]
	s_addc_u32 s43, s43, 0
	s_add_i32 s48, s55, s56
	global_load_lds_dwordx4 v[228:229], off
	v_lshl_add_u64 v[228:229], s[42:43], 0, v[134:135]
	s_mov_b32 m0, s48
	s_nop 0
	global_load_lds_dwordx4 v[228:229], off
	v_lshl_add_u64 v[228:229], s[42:43], 0, v[130:131]
	s_add_i32 m0, s48, 0x2000
	s_nop 0
	global_load_lds_dwordx4 v[228:229], off
	v_lshl_add_u64 v[228:229], v[240:241], 0, s[16:17]
	s_mov_b32 m0, s63
	s_nop 0
	global_load_lds_dwordx4 v[228:229], off
	v_lshl_add_u64 v[228:229], v[242:243], 0, s[16:17]
	s_mov_b32 m0, s64
	s_nop 0
	global_load_lds_dwordx4 v[228:229], off
	s_waitcnt vmcnt(8)
	s_waitcnt lgkmcnt(0)
	s_setprio 1
	s_barrier
	v_mfma_f32_16x16x32_bf16 v[62:65], v[142:145], v[178:181], v[62:65]
	v_mfma_f32_16x16x32_bf16 v[58:61], v[150:153], v[178:181], v[58:61]
	v_mfma_f32_16x16x32_bf16 v[46:49], v[142:145], v[204:207], v[46:49]
	v_mfma_f32_16x16x32_bf16 v[42:45], v[150:153], v[204:207], v[42:45]
	v_mfma_f32_16x16x32_bf16 v[30:33], v[142:145], v[212:215], v[30:33]
	v_mfma_f32_16x16x32_bf16 v[26:29], v[150:153], v[212:215], v[26:29]
	v_mfma_f32_16x16x32_bf16 v[14:17], v[142:145], v[220:223], v[14:17]
	v_mfma_f32_16x16x32_bf16 v[10:13], v[150:153], v[220:223], v[10:13]
	s_add_i32 s53, s53, 2
	s_add_u32 s40, s40, 0x100
	s_addc_u32 s41, s41, 0
	s_add_u32 s51, s51, 0x100
	s_addc_u32 s52, s52, 0
	v_mfma_f32_16x16x32_bf16 v[62:65], v[146:149], v[182:185], v[62:65]
	v_mfma_f32_16x16x32_bf16 v[58:61], v[154:157], v[182:185], v[58:61]
	v_mfma_f32_16x16x32_bf16 v[46:49], v[146:149], v[208:211], v[46:49]
	v_mfma_f32_16x16x32_bf16 v[42:45], v[154:157], v[208:211], v[42:45]
	v_mfma_f32_16x16x32_bf16 v[30:33], v[146:149], v[216:219], v[30:33]
	v_mfma_f32_16x16x32_bf16 v[26:29], v[154:157], v[216:219], v[26:29]
	v_mfma_f32_16x16x32_bf16 v[14:17], v[146:149], v[224:227], v[14:17]
	v_mfma_f32_16x16x32_bf16 v[10:13], v[154:157], v[224:227], v[10:13]
	v_mfma_f32_16x16x32_bf16 v[54:57], v[162:165], v[178:181], v[54:57]
	v_mfma_f32_16x16x32_bf16 v[50:53], v[170:173], v[178:181], v[50:53]
	v_mfma_f32_16x16x32_bf16 v[38:41], v[162:165], v[204:207], v[38:41]
	v_mfma_f32_16x16x32_bf16 v[34:37], v[170:173], v[204:207], v[34:37]
	v_mfma_f32_16x16x32_bf16 v[22:25], v[162:165], v[212:215], v[22:25]
	v_mfma_f32_16x16x32_bf16 v[18:21], v[170:173], v[212:215], v[18:21]
	v_mfma_f32_16x16x32_bf16 v[6:9], v[162:165], v[220:223], v[6:9]
	v_mfma_f32_16x16x32_bf16 v[2:5], v[170:173], v[220:223], v[2:5]
	v_mfma_f32_16x16x32_bf16 v[54:57], v[166:169], v[182:185], v[54:57]
	v_mfma_f32_16x16x32_bf16 v[50:53], v[174:177], v[182:185], v[50:53]
	v_mfma_f32_16x16x32_bf16 v[38:41], v[166:169], v[208:211], v[38:41]
	v_mfma_f32_16x16x32_bf16 v[34:37], v[174:177], v[208:211], v[34:37]
	v_mfma_f32_16x16x32_bf16 v[22:25], v[166:169], v[216:219], v[22:25]
	v_mfma_f32_16x16x32_bf16 v[18:21], v[174:177], v[216:219], v[18:21]
	v_mfma_f32_16x16x32_bf16 v[6:9], v[166:169], v[224:227], v[6:9]
	v_mfma_f32_16x16x32_bf16 v[2:5], v[174:177], v[224:227], v[2:5]
	s_barrier
	s_setprio 0
	s_cmp_gt_u32 s53, 13
	s_cbranch_scc0 .LBB0_1186
	s_and_b64 vcc, exec, s[18:19]
	s_cbranch_vccz .LBB0_1189
	s_barrier
